# X44: X39 plus constant LDS slot offsets folded into their single scalar add in the K-loop load segments (10 fewer scalar instructions per set of loops)
# speedup vs baseline: 1.0002x; 1.0002x over previous
; #define PG8_STAGE(bufoff, gbase, voff) do { _Pragma("unroll") for (int _i = 0; _i < 2; ++_i) \
;         __builtin_amdgcn_global_load_lds((const unsigned*)((const char*)(gbase) + (voff)[_i]), (PG8_LAS unsigned*)(lds + (bufoff) + ldsw + _i * 8192), 16, 0, 0); } while (0)
; #define PG8_LDA(dst, b, h) do { _Pragma("unroll") for (int m = 0; m < 4; ++m) _Pragma("unroll") for (int k = 0; k < 2; ++k) dst[m][k] = *(const PG8_LAS bf16x8*)(lds + PG8_SA(b, h) + aoff + m * 2048 + k * 1024); } while (0)
; #define PG8_LDB(dst, b, h) do { _Pragma("unroll") for (int n = 0; n < 2; ++n) _Pragma("unroll") for (int k = 0; k < 2; ++k) dst[n][k] = *(const PG8_LAS bf16x8*)(lds + PG8_SB(b, h) + boff + n * 2048 + k * 1024); } while (0)
; #define PG8_WAIT_V(n) asm volatile("s_waitcnt vmcnt(" #n ")" ::: "memory")
; #define PG8_WAIT_L(n) asm volatile("s_waitcnt lgkmcnt(" #n ")" ::: "memory")
; #define PG8_BAR __builtin_amdgcn_s_barrier()
; #define PG8_SCHED __builtin_amdgcn_sched_barrier(0)
; template <class Epi, class Sched, bool ALIGN_EPI = false, bool SP2 = false>
; __device__ __forceinline__ void gemm_phase(PG8_LAS unsigned char* lds, const Gemm g, const Sched& S, const Epi& E) {
;     ...
;         const char* nA = has_next ? (const char*)g.A + (size_t)nxt.pm * tstep : cA; const char* nB = has_next ? (const char*)g.Bt + (size_t)nxt.pn * tstep : cB;
;         for (int t = 0; t < nt; t += 2) {
;             const bool last = (t == nt - 2);
;             const char* a1 = cA + (size_t)(t + 1) * kstep;
;             const char* a2 = last ? nA : cA + (size_t)(t + 2) * kstep; const char* b2 = last ? nB : cB + (size_t)(t + 2) * kstep;
;             const char* a3 = a2 + kstep; const char* b3 = b2 + kstep;
;             if (last && has_next) S.a_ready(nxt);
;             if constexpr (SP2) {
;             PG8_LDB(B0, 0, 0); PG8_LDB(B1, 0, 1); PG8_SCHED; PG8_LDA(At, 0, 0); PG8_STAGE(PG8_SA(1, 1), a1 + hstep, voffA);
;             PG8_WAIT_V(8); PG8_WAIT_L(0); PG8_BAR; PG8_MMA(0, 0, At, B0); PG8_MMA(0, 1, At, B1); PG8_BAR; PG8_SCHED;
;             PG8_LDA(At, 0, 1); PG8_STAGE(PG8_SB(0, 0), b2, voffB); PG8_STAGE(PG8_SB(0, 1), b2 + hstep, voffB); PG8_STAGE(PG8_SA(0, 0), a2, voffA);
;             PG8_WAIT_V(8); PG8_WAIT_L(0); PG8_BAR; PG8_MMA(1, 0, At, B0); PG8_MMA(1, 1, At, B1); PG8_BAR; PG8_SCHED;
.LBB0_216:
	ds_read_b128 v[144:147], v152
	ds_read_b128 v[148:151], v152 offset:1024
	ds_read_b128 v[168:171], v152 offset:2048
	ds_read_b128 v[172:175], v152 offset:3072
	ds_read_b128 v[176:179], v153
	ds_read_b128 v[180:183], v153 offset:1024
	ds_read_b128 v[184:187], v153 offset:2048
	ds_read_b128 v[188:191], v153 offset:3072
	ds_read_b128 v[212:215], v157
	ds_read_b128 v[216:219], v157 offset:1024
	ds_read_b128 v[220:223], v157 offset:2048
	ds_read_b128 v[224:227], v157 offset:3072
	ds_read_b128 v[228:231], v157 offset:4096
	ds_read_b128 v[232:235], v157 offset:5120
	ds_read_b128 v[236:239], v157 offset:6144
	ds_read_b128 v[240:243], v157 offset:7168
	s_add_i32 m0, s66, 0xc000
	s_add_u32 s22, s54, 0xfff80080
	s_addc_u32 s23, s55, -1
	global_load_lds_dwordx4 v140, s[54:55]
	s_add_i32 m0, s66, 0xe000
	global_load_lds_dwordx4 v142, s[54:55]
	s_cmp_eq_u32 s20, 28
	s_cselect_b32 s57, s47, s23
	s_cselect_b32 s56, vcc_lo, s22
	s_cselect_b32 s23, s49, s77
	s_cselect_b32 s22, vcc_hi, s71
	s_waitcnt vmcnt(8)
	s_waitcnt lgkmcnt(0)
	s_barrier
	v_mfma_f32_16x16x32_bf16 v[126:129], v[144:147], v[212:215], v[126:129]
	v_mfma_f32_16x16x32_bf16 v[126:129], v[148:151], v[216:219], v[126:129]
	v_mfma_f32_16x16x32_bf16 v[118:121], v[168:171], v[212:215], v[118:121]
	v_mfma_f32_16x16x32_bf16 v[118:121], v[172:175], v[216:219], v[118:121]
	v_mfma_f32_16x16x32_bf16 v[130:133], v[176:179], v[212:215], v[130:133]
	v_mfma_f32_16x16x32_bf16 v[130:133], v[180:183], v[216:219], v[130:133]
	v_mfma_f32_16x16x32_bf16 v[122:125], v[184:187], v[212:215], v[122:125]
	v_mfma_f32_16x16x32_bf16 v[122:125], v[188:191], v[216:219], v[122:125]
	v_mfma_f32_16x16x32_bf16 v[106:109], v[184:187], v[220:223], v[106:109]
	v_mfma_f32_16x16x32_bf16 v[106:109], v[188:191], v[224:227], v[106:109]
	v_mfma_f32_16x16x32_bf16 v[114:117], v[176:179], v[220:223], v[114:117]
	v_mfma_f32_16x16x32_bf16 v[114:117], v[180:183], v[224:227], v[114:117]
	v_mfma_f32_16x16x32_bf16 v[102:105], v[168:171], v[220:223], v[102:105]
	v_mfma_f32_16x16x32_bf16 v[102:105], v[172:175], v[224:227], v[102:105]
	v_mfma_f32_16x16x32_bf16 v[110:113], v[144:147], v[220:223], v[110:113]
	v_mfma_f32_16x16x32_bf16 v[110:113], v[148:151], v[224:227], v[110:113]
	v_mfma_f32_16x16x32_bf16 v[94:97], v[144:147], v[228:231], v[94:97]
	v_mfma_f32_16x16x32_bf16 v[94:97], v[148:151], v[232:235], v[94:97]
	v_mfma_f32_16x16x32_bf16 v[86:89], v[168:171], v[228:231], v[86:89]
	v_mfma_f32_16x16x32_bf16 v[86:89], v[172:175], v[232:235], v[86:89]
	v_mfma_f32_16x16x32_bf16 v[98:101], v[176:179], v[228:231], v[98:101]
	v_mfma_f32_16x16x32_bf16 v[98:101], v[180:183], v[232:235], v[98:101]
	v_mfma_f32_16x16x32_bf16 v[90:93], v[184:187], v[228:231], v[90:93]
	v_mfma_f32_16x16x32_bf16 v[90:93], v[188:191], v[232:235], v[90:93]
	v_mfma_f32_16x16x32_bf16 v[74:77], v[184:187], v[236:239], v[74:77]
	v_mfma_f32_16x16x32_bf16 v[74:77], v[188:191], v[240:243], v[74:77]
	v_mfma_f32_16x16x32_bf16 v[82:85], v[176:179], v[236:239], v[82:85]
	v_mfma_f32_16x16x32_bf16 v[82:85], v[180:183], v[240:243], v[82:85]
	v_mfma_f32_16x16x32_bf16 v[70:73], v[168:171], v[236:239], v[70:73]
	v_mfma_f32_16x16x32_bf16 v[70:73], v[172:175], v[240:243], v[70:73]
	v_mfma_f32_16x16x32_bf16 v[78:81], v[144:147], v[236:239], v[78:81]
	v_mfma_f32_16x16x32_bf16 v[78:81], v[148:151], v[240:243], v[78:81]
	s_barrier
	ds_read_b128 v[212:215], v157 offset:16384
	ds_read_b128 v[216:219], v157 offset:17408
	ds_read_b128 v[220:223], v157 offset:18432
	ds_read_b128 v[224:227], v157 offset:19456
	ds_read_b128 v[228:231], v157 offset:20480
	ds_read_b128 v[232:235], v157 offset:21504
	ds_read_b128 v[236:239], v157 offset:22528
	ds_read_b128 v[240:243], v157 offset:23552
	s_add_i32 s5, s65, 0x10000
	s_mov_b32 m0, s5
	s_add_u32 s34, s22, 0x80000
	s_addc_u32 s35, s23, 0
	global_load_lds_dwordx4 v4, s[22:23]
	s_add_i32 m0, s5, 0x2000
	s_add_i32 s4, s65, 0x14000
	global_load_lds_dwordx4 v2, s[22:23]
	s_mov_b32 m0, s4
	s_nop 0
	global_load_lds_dwordx4 v4, s[34:35]
	s_add_i32 m0, s4, 0x2000
	s_nop 0
	global_load_lds_dwordx4 v2, s[34:35]
	s_mov_b32 m0, s66
	s_nop 0
	global_load_lds_dwordx4 v136, s[56:57]
	s_mov_b32 m0, s67
	s_nop 0
	global_load_lds_dwordx4 v134, s[56:57]
	s_waitcnt vmcnt(8)
	s_waitcnt lgkmcnt(0)
	s_barrier
	v_mfma_f32_16x16x32_bf16 v[62:65], v[144:147], v[212:215], v[62:65]
	v_mfma_f32_16x16x32_bf16 v[62:65], v[148:151], v[216:219], v[62:65]
	v_mfma_f32_16x16x32_bf16 v[54:57], v[168:171], v[212:215], v[54:57]
	v_mfma_f32_16x16x32_bf16 v[54:57], v[172:175], v[216:219], v[54:57]
	v_mfma_f32_16x16x32_bf16 v[66:69], v[176:179], v[212:215], v[66:69]
	v_mfma_f32_16x16x32_bf16 v[66:69], v[180:183], v[216:219], v[66:69]
	v_mfma_f32_16x16x32_bf16 v[58:61], v[184:187], v[212:215], v[58:61]
	v_mfma_f32_16x16x32_bf16 v[58:61], v[188:191], v[216:219], v[58:61]
	v_mfma_f32_16x16x32_bf16 v[42:45], v[184:187], v[220:223], v[42:45]
	v_mfma_f32_16x16x32_bf16 v[42:45], v[188:191], v[224:227], v[42:45]
	v_mfma_f32_16x16x32_bf16 v[50:53], v[176:179], v[220:223], v[50:53]
	v_mfma_f32_16x16x32_bf16 v[50:53], v[180:183], v[224:227], v[50:53]
	v_mfma_f32_16x16x32_bf16 v[38:41], v[168:171], v[220:223], v[38:41]
	v_mfma_f32_16x16x32_bf16 v[38:41], v[172:175], v[224:227], v[38:41]
	v_mfma_f32_16x16x32_bf16 v[46:49], v[144:147], v[220:223], v[46:49]
	v_mfma_f32_16x16x32_bf16 v[46:49], v[148:151], v[224:227], v[46:49]
	v_mfma_f32_16x16x32_bf16 v[30:33], v[144:147], v[228:231], v[30:33]
	v_mfma_f32_16x16x32_bf16 v[30:33], v[148:151], v[232:235], v[30:33]
	v_mfma_f32_16x16x32_bf16 v[22:25], v[168:171], v[228:231], v[22:25]
	v_mfma_f32_16x16x32_bf16 v[22:25], v[172:175], v[232:235], v[22:25]
	v_mfma_f32_16x16x32_bf16 v[34:37], v[176:179], v[228:231], v[34:37]
	v_mfma_f32_16x16x32_bf16 v[34:37], v[180:183], v[232:235], v[34:37]
	v_mfma_f32_16x16x32_bf16 v[26:29], v[184:187], v[228:231], v[26:29]
	v_mfma_f32_16x16x32_bf16 v[26:29], v[188:191], v[232:235], v[26:29]
	v_mfma_f32_16x16x32_bf16 v[10:13], v[184:187], v[236:239], v[10:13]
	v_mfma_f32_16x16x32_bf16 v[10:13], v[188:191], v[240:243], v[10:13]
	v_mfma_f32_16x16x32_bf16 v[18:21], v[176:179], v[236:239], v[18:21]
	v_mfma_f32_16x16x32_bf16 v[18:21], v[180:183], v[240:243], v[18:21]
	v_mfma_f32_16x16x32_bf16 v[6:9], v[168:171], v[236:239], v[6:9]
	v_mfma_f32_16x16x32_bf16 v[6:9], v[172:175], v[240:243], v[6:9]
	v_mfma_f32_16x16x32_bf16 v[14:17], v[144:147], v[236:239], v[14:17]
	v_mfma_f32_16x16x32_bf16 v[14:17], v[148:151], v[240:243], v[14:17]
	s_barrier
; #define PG8_STAGE(bufoff, gbase, voff) do { _Pragma("unroll") for (int _i = 0; _i < 2; ++_i) \
;         __builtin_amdgcn_global_load_lds((const unsigned*)((const char*)(gbase) + (voff)[_i]), (PG8_LAS unsigned*)(lds + (bufoff) + ldsw + _i * 8192), 16, 0, 0); } while (0)
; #define PG8_LDA(dst, b, h) do { _Pragma("unroll") for (int m = 0; m < 4; ++m) _Pragma("unroll") for (int k = 0; k < 2; ++k) dst[m][k] = *(const PG8_LAS bf16x8*)(lds + PG8_SA(b, h) + aoff + m * 2048 + k * 1024); } while (0)
; #define PG8_LDB(dst, b, h) do { _Pragma("unroll") for (int n = 0; n < 2; ++n) _Pragma("unroll") for (int k = 0; k < 2; ++k) dst[n][k] = *(const PG8_LAS bf16x8*)(lds + PG8_SB(b, h) + boff + n * 2048 + k * 1024); } while (0)
; #define PG8_MMA(ai, bj, At, Bt) do { __builtin_amdgcn_s_setprio(1); _Pragma("unroll") for (int m = 0; m < 4; ++m) _Pragma("unroll") for (int n = 0; n < 2; ++n) _Pragma("unroll") for (int k = 0; k < 2; ++k) \
;         acc[ai][bj][m][n] = __builtin_amdgcn_mfma_f32_16x16x32_bf16(Bt[n][k], At[m][k], acc[ai][bj][m][n], 0, 0, 0); __builtin_amdgcn_s_setprio(0); } while (0)
; #define PG8_WAIT_V(n) asm volatile("s_waitcnt vmcnt(" #n ")" ::: "memory")
; #define PG8_WAIT_L(n) asm volatile("s_waitcnt lgkmcnt(" #n ")" ::: "memory")
; #define PG8_BAR __builtin_amdgcn_s_barrier()
; #define PG8_SCHED __builtin_amdgcn_sched_barrier(0)
; template <class Epi, class Sched, bool ALIGN_EPI = false, bool SP2 = false>
; __device__ __forceinline__ void gemm_phase(PG8_LAS unsigned char* lds, const Gemm g, const Sched& S, const Epi& E) {
;     ...
;         for (int t = 0; t < nt; t += 2) {
;             const bool last = (t == nt - 2);
;             const char* a1 = cA + (size_t)(t + 1) * kstep;
;             const char* a2 = last ? nA : cA + (size_t)(t + 2) * kstep; const char* b2 = last ? nB : cB + (size_t)(t + 2) * kstep;
;     ...
;             PG8_LDB(B0, 1, 0); PG8_LDB(B1, 1, 1); PG8_SCHED; PG8_LDA(At, 1, 0); PG8_STAGE(PG8_SA(0, 1), a2 + hstep, voffA);
;             PG8_WAIT_V(8); PG8_WAIT_L(0); PG8_BAR; PG8_MMA(0, 0, At, B0); PG8_MMA(0, 1, At, B1); PG8_BAR; PG8_SCHED;
;             PG8_LDA(At, 1, 1); PG8_STAGE(PG8_SB(1, 0), b3, voffB); PG8_STAGE(PG8_SB(1, 1), b3 + hstep, voffB); PG8_STAGE(PG8_SA(1, 0), a3, voffA);
;             PG8_WAIT_V(8); PG8_WAIT_L(0); PG8_BAR; PG8_MMA(1, 0, At, B0); PG8_MMA(1, 1, At, B1); PG8_BAR; PG8_SCHED;
	ds_read_b128 v[144:147], v192
	ds_read_b128 v[148:151], v192 offset:1024
	ds_read_b128 v[168:171], v192 offset:2048
	ds_read_b128 v[172:175], v192 offset:3072
	ds_read_b128 v[176:179], v193
	ds_read_b128 v[180:183], v193 offset:1024
	ds_read_b128 v[184:187], v193 offset:2048
	ds_read_b128 v[188:191], v193 offset:3072
	ds_read_b128 v[212:215], v157 offset:32768
	ds_read_b128 v[216:219], v157 offset:33792
	ds_read_b128 v[220:223], v157 offset:34816
	ds_read_b128 v[224:227], v157 offset:35840
	ds_read_b128 v[228:231], v157 offset:36864
	ds_read_b128 v[232:235], v157 offset:37888
	ds_read_b128 v[236:239], v157 offset:38912
	ds_read_b128 v[240:243], v157 offset:39936
	s_add_u32 s34, s56, 0x80000
	s_addc_u32 s35, s57, 0
	s_mov_b32 m0, s60
	global_load_lds_dwordx4 v136, s[34:35]
	s_mov_b32 m0, s2
	s_add_i32 s5, 0, 0x1c000
	global_load_lds_dwordx4 v134, s[34:35]
	s_waitcnt vmcnt(8)
	s_waitcnt lgkmcnt(0)
	s_barrier
	v_mfma_f32_16x16x32_bf16 v[126:129], v[144:147], v[212:215], v[126:129]
	v_mfma_f32_16x16x32_bf16 v[126:129], v[148:151], v[216:219], v[126:129]
	v_mfma_f32_16x16x32_bf16 v[118:121], v[168:171], v[212:215], v[118:121]
	v_mfma_f32_16x16x32_bf16 v[118:121], v[172:175], v[216:219], v[118:121]
	v_mfma_f32_16x16x32_bf16 v[130:133], v[176:179], v[212:215], v[130:133]
	v_mfma_f32_16x16x32_bf16 v[130:133], v[180:183], v[216:219], v[130:133]
	v_mfma_f32_16x16x32_bf16 v[122:125], v[184:187], v[212:215], v[122:125]
	v_mfma_f32_16x16x32_bf16 v[122:125], v[188:191], v[216:219], v[122:125]
	v_mfma_f32_16x16x32_bf16 v[106:109], v[184:187], v[220:223], v[106:109]
	v_mfma_f32_16x16x32_bf16 v[106:109], v[188:191], v[224:227], v[106:109]
	v_mfma_f32_16x16x32_bf16 v[114:117], v[176:179], v[220:223], v[114:117]
	v_mfma_f32_16x16x32_bf16 v[114:117], v[180:183], v[224:227], v[114:117]
	v_mfma_f32_16x16x32_bf16 v[102:105], v[168:171], v[220:223], v[102:105]
	v_mfma_f32_16x16x32_bf16 v[102:105], v[172:175], v[224:227], v[102:105]
	v_mfma_f32_16x16x32_bf16 v[110:113], v[144:147], v[220:223], v[110:113]
	v_mfma_f32_16x16x32_bf16 v[110:113], v[148:151], v[224:227], v[110:113]
	v_mfma_f32_16x16x32_bf16 v[94:97], v[144:147], v[228:231], v[94:97]
	v_mfma_f32_16x16x32_bf16 v[94:97], v[148:151], v[232:235], v[94:97]
	v_mfma_f32_16x16x32_bf16 v[86:89], v[168:171], v[228:231], v[86:89]
	v_mfma_f32_16x16x32_bf16 v[86:89], v[172:175], v[232:235], v[86:89]
	v_mfma_f32_16x16x32_bf16 v[98:101], v[176:179], v[228:231], v[98:101]
	v_mfma_f32_16x16x32_bf16 v[98:101], v[180:183], v[232:235], v[98:101]
	v_mfma_f32_16x16x32_bf16 v[90:93], v[184:187], v[228:231], v[90:93]
	v_mfma_f32_16x16x32_bf16 v[90:93], v[188:191], v[232:235], v[90:93]
	v_mfma_f32_16x16x32_bf16 v[74:77], v[184:187], v[236:239], v[74:77]
	v_mfma_f32_16x16x32_bf16 v[74:77], v[188:191], v[240:243], v[74:77]
	v_mfma_f32_16x16x32_bf16 v[82:85], v[176:179], v[236:239], v[82:85]
	v_mfma_f32_16x16x32_bf16 v[82:85], v[180:183], v[240:243], v[82:85]
	v_mfma_f32_16x16x32_bf16 v[70:73], v[168:171], v[236:239], v[70:73]
	v_mfma_f32_16x16x32_bf16 v[70:73], v[172:175], v[240:243], v[70:73]
	v_mfma_f32_16x16x32_bf16 v[78:81], v[144:147], v[236:239], v[78:81]
	v_mfma_f32_16x16x32_bf16 v[78:81], v[148:151], v[240:243], v[78:81]
	s_barrier
	ds_read_b128 v[212:215], v157 offset:49152
	ds_read_b128 v[216:219], v157 offset:50176
	ds_read_b128 v[220:223], v157 offset:51200
	ds_read_b128 v[224:227], v157 offset:52224
	ds_read_b128 v[228:231], v157 offset:53248
	ds_read_b128 v[232:235], v157 offset:54272
	ds_read_b128 v[236:239], v157 offset:55296
	ds_read_b128 v[240:243], v157 offset:56320
	s_add_i32 s4, s65, 0x18000
	s_add_i32 m0, s4, 0xffffff80
	s_nop 0
	global_load_lds_dwordx4 v4, s[22:23] offset:128
	s_add_i32 m0, s4, 0x1f80
	s_add_i32 s4, s5, s65
	global_load_lds_dwordx4 v2, s[22:23] offset:128
	s_add_u32 s22, s22, 0x80080
	s_addc_u32 s23, s23, 0
	s_mov_b32 m0, s4
	s_nop 0
	global_load_lds_dwordx4 v4, s[22:23]
	s_add_i32 m0, s4, 0x2000
	s_nop 0
	global_load_lds_dwordx4 v2, s[22:23]
	s_add_i32 m0, s3, 0xffffff80
	s_nop 0
	global_load_lds_dwordx4 v136, s[56:57] offset:128
	s_add_i32 m0, s75, 0xffffff80
	s_nop 0
	global_load_lds_dwordx4 v134, s[56:57] offset:128
	s_waitcnt vmcnt(8)
	s_waitcnt lgkmcnt(0)
	s_barrier
	v_mfma_f32_16x16x32_bf16 v[62:65], v[144:147], v[212:215], v[62:65]
	v_mfma_f32_16x16x32_bf16 v[62:65], v[148:151], v[216:219], v[62:65]
	v_mfma_f32_16x16x32_bf16 v[54:57], v[168:171], v[212:215], v[54:57]
	v_mfma_f32_16x16x32_bf16 v[54:57], v[172:175], v[216:219], v[54:57]
	v_mfma_f32_16x16x32_bf16 v[66:69], v[176:179], v[212:215], v[66:69]
	v_mfma_f32_16x16x32_bf16 v[66:69], v[180:183], v[216:219], v[66:69]
	v_mfma_f32_16x16x32_bf16 v[58:61], v[184:187], v[212:215], v[58:61]
	v_mfma_f32_16x16x32_bf16 v[58:61], v[188:191], v[216:219], v[58:61]
	v_mfma_f32_16x16x32_bf16 v[42:45], v[184:187], v[220:223], v[42:45]
	v_mfma_f32_16x16x32_bf16 v[42:45], v[188:191], v[224:227], v[42:45]
	v_mfma_f32_16x16x32_bf16 v[50:53], v[176:179], v[220:223], v[50:53]
	v_mfma_f32_16x16x32_bf16 v[50:53], v[180:183], v[224:227], v[50:53]
	v_mfma_f32_16x16x32_bf16 v[38:41], v[168:171], v[220:223], v[38:41]
	v_mfma_f32_16x16x32_bf16 v[38:41], v[172:175], v[224:227], v[38:41]
	v_mfma_f32_16x16x32_bf16 v[46:49], v[144:147], v[220:223], v[46:49]
	v_mfma_f32_16x16x32_bf16 v[46:49], v[148:151], v[224:227], v[46:49]
	v_mfma_f32_16x16x32_bf16 v[30:33], v[144:147], v[228:231], v[30:33]
	v_mfma_f32_16x16x32_bf16 v[30:33], v[148:151], v[232:235], v[30:33]
	v_mfma_f32_16x16x32_bf16 v[22:25], v[168:171], v[228:231], v[22:25]
	v_mfma_f32_16x16x32_bf16 v[22:25], v[172:175], v[232:235], v[22:25]
	v_mfma_f32_16x16x32_bf16 v[34:37], v[176:179], v[228:231], v[34:37]
	v_mfma_f32_16x16x32_bf16 v[34:37], v[180:183], v[232:235], v[34:37]
	v_mfma_f32_16x16x32_bf16 v[26:29], v[184:187], v[228:231], v[26:29]
	v_mfma_f32_16x16x32_bf16 v[26:29], v[188:191], v[232:235], v[26:29]
	v_mfma_f32_16x16x32_bf16 v[10:13], v[184:187], v[236:239], v[10:13]
	v_mfma_f32_16x16x32_bf16 v[10:13], v[188:191], v[240:243], v[10:13]
	v_mfma_f32_16x16x32_bf16 v[18:21], v[176:179], v[236:239], v[18:21]
	v_mfma_f32_16x16x32_bf16 v[18:21], v[180:183], v[240:243], v[18:21]
	v_mfma_f32_16x16x32_bf16 v[6:9], v[168:171], v[236:239], v[6:9]
	v_mfma_f32_16x16x32_bf16 v[6:9], v[172:175], v[240:243], v[6:9]
	v_mfma_f32_16x16x32_bf16 v[14:17], v[144:147], v[236:239], v[14:17]
	v_mfma_f32_16x16x32_bf16 v[14:17], v[148:151], v[240:243], v[14:17]
	s_barrier
	s_add_i32 s20, s20, 2
	s_add_u32 s54, s54, 0x100
	s_addc_u32 s55, s55, 0
	s_add_u32 s71, s71, 0x100
	s_addc_u32 s77, s77, 0
	s_cmp_gt_u32 s20, 29
	s_cbranch_scc0 .LBB0_216
	s_and_b64 vcc, exec, s[44:45]
	s_movk_i32 s77, 0x6000
	s_mov_b32 s71, 0x44800000
	s_cbranch_vccz .LBB0_219
	s_barrier

; #define PG8_STAGE(bufoff, gbase, voff) do { _Pragma("unroll") for (int _i = 0; _i < 2; ++_i) \
;         __builtin_amdgcn_global_load_lds((const unsigned*)((const char*)(gbase) + (voff)[_i]), (PG8_LAS unsigned*)(lds + (bufoff) + ldsw + _i * 8192), 16, 0, 0); } while (0)
; #define PG8_LDA(dst, b, h) do { _Pragma("unroll") for (int m = 0; m < 4; ++m) _Pragma("unroll") for (int k = 0; k < 2; ++k) dst[m][k] = *(const PG8_LAS bf16x8*)(lds + PG8_SA(b, h) + aoff + m * 2048 + k * 1024); } while (0)
; #define PG8_LDB(dst, b, h) do { _Pragma("unroll") for (int n = 0; n < 2; ++n) _Pragma("unroll") for (int k = 0; k < 2; ++k) dst[n][k] = *(const PG8_LAS bf16x8*)(lds + PG8_SB(b, h) + boff + n * 2048 + k * 1024); } while (0)
; #define PG8_MMA(ai, bj, At, Bt) do { __builtin_amdgcn_s_setprio(1); _Pragma("unroll") for (int m = 0; m < 4; ++m) _Pragma("unroll") for (int n = 0; n < 2; ++n) _Pragma("unroll") for (int k = 0; k < 2; ++k) \
;         acc[ai][bj][m][n] = __builtin_amdgcn_mfma_f32_16x16x32_bf16(Bt[n][k], At[m][k], acc[ai][bj][m][n], 0, 0, 0); __builtin_amdgcn_s_setprio(0); } while (0)
; #define PG8_WAIT_V(n) asm volatile("s_waitcnt vmcnt(" #n ")" ::: "memory")
; #define PG8_WAIT_L(n) asm volatile("s_waitcnt lgkmcnt(" #n ")" ::: "memory")
; template <class Epi, class Sched, bool ALIGN_EPI = false, bool SP2 = false>
; __device__ __forceinline__ void gemm_phase(PG8_LAS unsigned char* lds, const Gemm g, const Sched& S, const Epi& E) {
;     ...
;             const bool last = (t == nt - 2);
;             const char* a1 = cA + (size_t)(t + 1) * kstep;
;             const char* a2 = last ? nA : cA + (size_t)(t + 2) * kstep; const char* b2 = last ? nB : cB + (size_t)(t + 2) * kstep;
;             const char* a3 = a2 + kstep; const char* b3 = b2 + kstep;
;             if (last && has_next) S.a_ready(nxt);
;             if constexpr (SP2) {
;             PG8_LDB(B0, 0, 0); PG8_LDB(B1, 0, 1); PG8_SCHED; PG8_LDA(At, 0, 0); PG8_STAGE(PG8_SA(1, 1), a1 + hstep, voffA);
;             PG8_WAIT_V(8); PG8_WAIT_L(0); PG8_BAR; PG8_MMA(0, 0, At, B0); PG8_MMA(0, 1, At, B1); PG8_BAR; PG8_SCHED;
;             PG8_LDA(At, 0, 1); PG8_STAGE(PG8_SB(0, 0), b2, voffB); PG8_STAGE(PG8_SB(0, 1), b2 + hstep, voffB); PG8_STAGE(PG8_SA(0, 0), a2, voffA);
;             PG8_WAIT_V(8); PG8_WAIT_L(0); PG8_BAR; PG8_MMA(1, 0, At, B0); PG8_MMA(1, 1, At, B1); PG8_BAR; PG8_SCHED;
.LBB0_299:
	s_add_u32 s50, s22, 0x100
	s_addc_u32 s51, s23, 0
	s_cmpk_eq_i32 s20, 0x54
	s_cselect_b32 s55, s41, s51
	s_cselect_b32 s54, s40, s50
	s_cselect_b32 s53, s49, s69
	s_cselect_b32 s52, s48, s33
	ds_read_b128 v[134:137], v236
	ds_read_b128 v[138:141], v236 offset:1024
	ds_read_b128 v[142:145], v236 offset:2048
	ds_read_b128 v[146:149], v236 offset:3072
	ds_read_b128 v[150:153], v237
	ds_read_b128 v[154:157], v237 offset:1024
	ds_read_b128 v[176:179], v237 offset:2048
	ds_read_b128 v[180:183], v237 offset:3072
	s_add_i32 m0, s56, 0xc000
	ds_read_b128 v[184:187], v188
	ds_read_b128 v[190:193], v188 offset:1024
	ds_read_b128 v[212:215], v188 offset:2048
	ds_read_b128 v[216:219], v188 offset:3072
	ds_read_b128 v[220:223], v188 offset:4096
	ds_read_b128 v[224:227], v188 offset:5120
	ds_read_b128 v[228:231], v188 offset:6144
	ds_read_b128 v[232:235], v188 offset:7168
	global_load_lds_dwordx4 v172, s[22:23]
	s_add_i32 m0, s56, 0xe000
	s_nop 0
	global_load_lds_dwordx4 v174, s[22:23]
	s_waitcnt vmcnt(8)
	s_waitcnt lgkmcnt(0)
	s_barrier
	v_mfma_f32_16x16x32_bf16 v[122:125], v[134:137], v[184:187], v[122:125]
	v_mfma_f32_16x16x32_bf16 v[122:125], v[138:141], v[190:193], v[122:125]
	v_mfma_f32_16x16x32_bf16 v[118:121], v[142:145], v[184:187], v[118:121]
	v_mfma_f32_16x16x32_bf16 v[118:121], v[146:149], v[190:193], v[118:121]
	v_mfma_f32_16x16x32_bf16 v[130:133], v[150:153], v[184:187], v[130:133]
	v_mfma_f32_16x16x32_bf16 v[130:133], v[154:157], v[190:193], v[130:133]
	v_mfma_f32_16x16x32_bf16 v[126:129], v[176:179], v[184:187], v[126:129]
	v_mfma_f32_16x16x32_bf16 v[126:129], v[180:183], v[190:193], v[126:129]
	v_mfma_f32_16x16x32_bf16 v[102:105], v[176:179], v[212:215], v[102:105]
	v_mfma_f32_16x16x32_bf16 v[102:105], v[180:183], v[216:219], v[102:105]
	v_mfma_f32_16x16x32_bf16 v[106:109], v[150:153], v[212:215], v[106:109]
	v_mfma_f32_16x16x32_bf16 v[106:109], v[154:157], v[216:219], v[106:109]
	v_mfma_f32_16x16x32_bf16 v[110:113], v[142:145], v[212:215], v[110:113]
	v_mfma_f32_16x16x32_bf16 v[110:113], v[146:149], v[216:219], v[110:113]
	v_mfma_f32_16x16x32_bf16 v[114:117], v[134:137], v[212:215], v[114:117]
	v_mfma_f32_16x16x32_bf16 v[114:117], v[138:141], v[216:219], v[114:117]
	v_mfma_f32_16x16x32_bf16 v[98:101], v[134:137], v[220:223], v[98:101]
	v_mfma_f32_16x16x32_bf16 v[98:101], v[138:141], v[224:227], v[98:101]
	v_mfma_f32_16x16x32_bf16 v[94:97], v[142:145], v[220:223], v[94:97]
	v_mfma_f32_16x16x32_bf16 v[94:97], v[146:149], v[224:227], v[94:97]
	v_mfma_f32_16x16x32_bf16 v[90:93], v[150:153], v[220:223], v[90:93]
	v_mfma_f32_16x16x32_bf16 v[90:93], v[154:157], v[224:227], v[90:93]
	v_mfma_f32_16x16x32_bf16 v[86:89], v[176:179], v[220:223], v[86:89]
	v_mfma_f32_16x16x32_bf16 v[86:89], v[180:183], v[224:227], v[86:89]
	v_mfma_f32_16x16x32_bf16 v[70:73], v[176:179], v[228:231], v[70:73]
	v_mfma_f32_16x16x32_bf16 v[70:73], v[180:183], v[232:235], v[70:73]
	v_mfma_f32_16x16x32_bf16 v[74:77], v[150:153], v[228:231], v[74:77]
	v_mfma_f32_16x16x32_bf16 v[74:77], v[154:157], v[232:235], v[74:77]
	v_mfma_f32_16x16x32_bf16 v[78:81], v[142:145], v[228:231], v[78:81]
	v_mfma_f32_16x16x32_bf16 v[78:81], v[146:149], v[232:235], v[78:81]
	v_mfma_f32_16x16x32_bf16 v[82:85], v[134:137], v[228:231], v[82:85]
	v_mfma_f32_16x16x32_bf16 v[82:85], v[138:141], v[232:235], v[82:85]
	s_barrier
	s_add_i32 s4, s24, 0x10000
	s_mov_b32 m0, s4
	ds_read_b128 v[184:187], v188 offset:16384
	ds_read_b128 v[190:193], v188 offset:17408
	ds_read_b128 v[212:215], v188 offset:18432
	ds_read_b128 v[216:219], v188 offset:19456
	ds_read_b128 v[220:223], v188 offset:20480
	ds_read_b128 v[224:227], v188 offset:21504
	ds_read_b128 v[228:231], v188 offset:22528
	ds_read_b128 v[232:235], v188 offset:23552
	global_load_lds_dwordx4 v4, s[52:53]
	s_add_i32 m0, s4, 0x2000
	s_add_u32 s22, s52, 0x160000
	s_addc_u32 s23, s53, 0
	s_add_i32 s4, s24, 0x14000
	global_load_lds_dwordx4 v170, s[52:53]
	s_mov_b32 m0, s4
	s_nop 0
	global_load_lds_dwordx4 v4, s[22:23]
	s_add_i32 m0, s4, 0x2000
	s_nop 0
	global_load_lds_dwordx4 v170, s[22:23]
	s_mov_b32 m0, s56
	s_nop 0
	global_load_lds_dwordx4 v2, s[54:55]
	s_mov_b32 m0, s57
	s_nop 0
	global_load_lds_dwordx4 v168, s[54:55]
	s_waitcnt vmcnt(8)
	s_waitcnt lgkmcnt(0)
	s_barrier
	v_mfma_f32_16x16x32_bf16 v[58:61], v[134:137], v[184:187], v[58:61]
	v_mfma_f32_16x16x32_bf16 v[58:61], v[138:141], v[190:193], v[58:61]
	v_mfma_f32_16x16x32_bf16 v[54:57], v[142:145], v[184:187], v[54:57]
	v_mfma_f32_16x16x32_bf16 v[54:57], v[146:149], v[190:193], v[54:57]
	v_mfma_f32_16x16x32_bf16 v[66:69], v[150:153], v[184:187], v[66:69]
	v_mfma_f32_16x16x32_bf16 v[66:69], v[154:157], v[190:193], v[66:69]
	v_mfma_f32_16x16x32_bf16 v[62:65], v[176:179], v[184:187], v[62:65]
	v_mfma_f32_16x16x32_bf16 v[62:65], v[180:183], v[190:193], v[62:65]
	v_mfma_f32_16x16x32_bf16 v[38:41], v[176:179], v[212:215], v[38:41]
	v_mfma_f32_16x16x32_bf16 v[38:41], v[180:183], v[216:219], v[38:41]
	v_mfma_f32_16x16x32_bf16 v[42:45], v[150:153], v[212:215], v[42:45]
	v_mfma_f32_16x16x32_bf16 v[42:45], v[154:157], v[216:219], v[42:45]
	v_mfma_f32_16x16x32_bf16 v[46:49], v[142:145], v[212:215], v[46:49]
	v_mfma_f32_16x16x32_bf16 v[46:49], v[146:149], v[216:219], v[46:49]
	v_mfma_f32_16x16x32_bf16 v[50:53], v[134:137], v[212:215], v[50:53]
	v_mfma_f32_16x16x32_bf16 v[50:53], v[138:141], v[216:219], v[50:53]
	v_mfma_f32_16x16x32_bf16 v[34:37], v[134:137], v[220:223], v[34:37]
	v_mfma_f32_16x16x32_bf16 v[34:37], v[138:141], v[224:227], v[34:37]
	v_mfma_f32_16x16x32_bf16 v[30:33], v[142:145], v[220:223], v[30:33]
	v_mfma_f32_16x16x32_bf16 v[30:33], v[146:149], v[224:227], v[30:33]
	v_mfma_f32_16x16x32_bf16 v[26:29], v[150:153], v[220:223], v[26:29]
	v_mfma_f32_16x16x32_bf16 v[26:29], v[154:157], v[224:227], v[26:29]
	v_mfma_f32_16x16x32_bf16 v[22:25], v[176:179], v[220:223], v[22:25]
	v_mfma_f32_16x16x32_bf16 v[22:25], v[180:183], v[224:227], v[22:25]
	v_mfma_f32_16x16x32_bf16 v[6:9], v[176:179], v[228:231], v[6:9]
	v_mfma_f32_16x16x32_bf16 v[6:9], v[180:183], v[232:235], v[6:9]
	v_mfma_f32_16x16x32_bf16 v[10:13], v[150:153], v[228:231], v[10:13]
	v_mfma_f32_16x16x32_bf16 v[10:13], v[154:157], v[232:235], v[10:13]
	v_mfma_f32_16x16x32_bf16 v[14:17], v[142:145], v[228:231], v[14:17]
	v_mfma_f32_16x16x32_bf16 v[14:17], v[146:149], v[232:235], v[14:17]
	v_mfma_f32_16x16x32_bf16 v[18:21], v[134:137], v[228:231], v[18:21]
	v_mfma_f32_16x16x32_bf16 v[18:21], v[138:141], v[232:235], v[18:21]
	s_barrier
; #define PG8_STAGE(bufoff, gbase, voff) do { _Pragma("unroll") for (int _i = 0; _i < 2; ++_i) \
;         __builtin_amdgcn_global_load_lds((const unsigned*)((const char*)(gbase) + (voff)[_i]), (PG8_LAS unsigned*)(lds + (bufoff) + ldsw + _i * 8192), 16, 0, 0); } while (0)
; #define PG8_LDA(dst, b, h) do { _Pragma("unroll") for (int m = 0; m < 4; ++m) _Pragma("unroll") for (int k = 0; k < 2; ++k) dst[m][k] = *(const PG8_LAS bf16x8*)(lds + PG8_SA(b, h) + aoff + m * 2048 + k * 1024); } while (0)
; #define PG8_LDB(dst, b, h) do { _Pragma("unroll") for (int n = 0; n < 2; ++n) _Pragma("unroll") for (int k = 0; k < 2; ++k) dst[n][k] = *(const PG8_LAS bf16x8*)(lds + PG8_SB(b, h) + boff + n * 2048 + k * 1024); } while (0)
; #define PG8_MMA(ai, bj, At, Bt) do { __builtin_amdgcn_s_setprio(1); _Pragma("unroll") for (int m = 0; m < 4; ++m) _Pragma("unroll") for (int n = 0; n < 2; ++n) _Pragma("unroll") for (int k = 0; k < 2; ++k) \
;         acc[ai][bj][m][n] = __builtin_amdgcn_mfma_f32_16x16x32_bf16(Bt[n][k], At[m][k], acc[ai][bj][m][n], 0, 0, 0); __builtin_amdgcn_s_setprio(0); } while (0)
; #define PG8_WAIT_V(n) asm volatile("s_waitcnt vmcnt(" #n ")" ::: "memory")
; #define PG8_WAIT_L(n) asm volatile("s_waitcnt lgkmcnt(" #n ")" ::: "memory")
; #define PG8_BAR __builtin_amdgcn_s_barrier()
; #define PG8_SCHED __builtin_amdgcn_sched_barrier(0)
; template <class Epi, class Sched, bool ALIGN_EPI = false, bool SP2 = false>
; __device__ __forceinline__ void gemm_phase(PG8_LAS unsigned char* lds, const Gemm g, const Sched& S, const Epi& E) {
;     ...
;         for (int t = 0; t < nt; t += 2) {
;             const bool last = (t == nt - 2);
;             const char* a1 = cA + (size_t)(t + 1) * kstep;
;             const char* a2 = last ? nA : cA + (size_t)(t + 2) * kstep; const char* b2 = last ? nB : cB + (size_t)(t + 2) * kstep;
;     ...
;             PG8_LDB(B0, 1, 0); PG8_LDB(B1, 1, 1); PG8_SCHED; PG8_LDA(At, 1, 0); PG8_STAGE(PG8_SA(0, 1), a2 + hstep, voffA);
;             PG8_WAIT_V(8); PG8_WAIT_L(0); PG8_BAR; PG8_MMA(0, 0, At, B0); PG8_MMA(0, 1, At, B1); PG8_BAR; PG8_SCHED;
;             PG8_LDA(At, 1, 1); PG8_STAGE(PG8_SB(1, 0), b3, voffB); PG8_STAGE(PG8_SB(1, 1), b3 + hstep, voffB); PG8_STAGE(PG8_SA(1, 0), a3, voffA);
;             PG8_WAIT_V(8); PG8_WAIT_L(0); PG8_BAR; PG8_MMA(1, 0, At, B0); PG8_MMA(1, 1, At, B1); PG8_BAR; PG8_SCHED;
	s_add_i32 s5, 0, 0x1c000
	ds_read_b128 v[134:137], v238
	ds_read_b128 v[138:141], v238 offset:1024
	ds_read_b128 v[142:145], v238 offset:2048
	ds_read_b128 v[146:149], v238 offset:3072
	ds_read_b128 v[150:153], v239
	ds_read_b128 v[154:157], v239 offset:1024
	ds_read_b128 v[176:179], v239 offset:2048
	ds_read_b128 v[180:183], v239 offset:3072
	s_add_u32 s22, s54, 0x160000
	s_addc_u32 s23, s55, 0
	s_mov_b32 m0, s59
	ds_read_b128 v[184:187], v188 offset:32768
	ds_read_b128 v[190:193], v188 offset:33792
	ds_read_b128 v[212:215], v188 offset:34816
	ds_read_b128 v[216:219], v188 offset:35840
	ds_read_b128 v[220:223], v188 offset:36864
	ds_read_b128 v[224:227], v188 offset:37888
	ds_read_b128 v[228:231], v188 offset:38912
	ds_read_b128 v[232:235], v188 offset:39936
	global_load_lds_dwordx4 v2, s[22:23]
	s_mov_b32 m0, s60
	s_nop 0
	global_load_lds_dwordx4 v168, s[22:23]
	s_waitcnt vmcnt(8)
	s_waitcnt lgkmcnt(0)
	s_barrier
	v_mfma_f32_16x16x32_bf16 v[122:125], v[134:137], v[184:187], v[122:125]
	v_mfma_f32_16x16x32_bf16 v[122:125], v[138:141], v[190:193], v[122:125]
	v_mfma_f32_16x16x32_bf16 v[118:121], v[142:145], v[184:187], v[118:121]
	v_mfma_f32_16x16x32_bf16 v[118:121], v[146:149], v[190:193], v[118:121]
	v_mfma_f32_16x16x32_bf16 v[130:133], v[150:153], v[184:187], v[130:133]
	v_mfma_f32_16x16x32_bf16 v[130:133], v[154:157], v[190:193], v[130:133]
	v_mfma_f32_16x16x32_bf16 v[126:129], v[176:179], v[184:187], v[126:129]
	v_mfma_f32_16x16x32_bf16 v[126:129], v[180:183], v[190:193], v[126:129]
	v_mfma_f32_16x16x32_bf16 v[102:105], v[176:179], v[212:215], v[102:105]
	v_mfma_f32_16x16x32_bf16 v[102:105], v[180:183], v[216:219], v[102:105]
	v_mfma_f32_16x16x32_bf16 v[106:109], v[150:153], v[212:215], v[106:109]
	v_mfma_f32_16x16x32_bf16 v[106:109], v[154:157], v[216:219], v[106:109]
	v_mfma_f32_16x16x32_bf16 v[110:113], v[142:145], v[212:215], v[110:113]
	v_mfma_f32_16x16x32_bf16 v[110:113], v[146:149], v[216:219], v[110:113]
	v_mfma_f32_16x16x32_bf16 v[114:117], v[134:137], v[212:215], v[114:117]
	v_mfma_f32_16x16x32_bf16 v[114:117], v[138:141], v[216:219], v[114:117]
	v_mfma_f32_16x16x32_bf16 v[98:101], v[134:137], v[220:223], v[98:101]
	v_mfma_f32_16x16x32_bf16 v[98:101], v[138:141], v[224:227], v[98:101]
	v_mfma_f32_16x16x32_bf16 v[94:97], v[142:145], v[220:223], v[94:97]
	v_mfma_f32_16x16x32_bf16 v[94:97], v[146:149], v[224:227], v[94:97]
	v_mfma_f32_16x16x32_bf16 v[90:93], v[150:153], v[220:223], v[90:93]
	v_mfma_f32_16x16x32_bf16 v[90:93], v[154:157], v[224:227], v[90:93]
	v_mfma_f32_16x16x32_bf16 v[86:89], v[176:179], v[220:223], v[86:89]
	v_mfma_f32_16x16x32_bf16 v[86:89], v[180:183], v[224:227], v[86:89]
	v_mfma_f32_16x16x32_bf16 v[70:73], v[176:179], v[228:231], v[70:73]
	v_mfma_f32_16x16x32_bf16 v[70:73], v[180:183], v[232:235], v[70:73]
	v_mfma_f32_16x16x32_bf16 v[74:77], v[150:153], v[228:231], v[74:77]
	v_mfma_f32_16x16x32_bf16 v[74:77], v[154:157], v[232:235], v[74:77]
	v_mfma_f32_16x16x32_bf16 v[78:81], v[142:145], v[228:231], v[78:81]
	v_mfma_f32_16x16x32_bf16 v[78:81], v[146:149], v[232:235], v[78:81]
	v_mfma_f32_16x16x32_bf16 v[82:85], v[134:137], v[228:231], v[82:85]
	v_mfma_f32_16x16x32_bf16 v[82:85], v[138:141], v[232:235], v[82:85]
	s_barrier
	s_add_i32 s4, s24, 0x18000
	s_add_i32 m0, s4, 0xffffff80
	ds_read_b128 v[184:187], v188 offset:49152
	ds_read_b128 v[190:193], v188 offset:50176
	ds_read_b128 v[212:215], v188 offset:51200
	ds_read_b128 v[216:219], v188 offset:52224
	ds_read_b128 v[220:223], v188 offset:53248
	ds_read_b128 v[224:227], v188 offset:54272
	ds_read_b128 v[228:231], v188 offset:55296
	ds_read_b128 v[232:235], v188 offset:56320
	global_load_lds_dwordx4 v4, s[52:53] offset:128
	s_add_i32 m0, s4, 0x1f80
	s_add_u32 s22, s52, 0x160080
	s_addc_u32 s23, s53, 0
	s_add_i32 s4, s5, s24
	global_load_lds_dwordx4 v170, s[52:53] offset:128
	s_mov_b32 m0, s4
	s_nop 0
	global_load_lds_dwordx4 v4, s[22:23]
	s_add_i32 m0, s4, 0x2000
	s_nop 0
	global_load_lds_dwordx4 v170, s[22:23]
	s_add_i32 m0, s61, 0xffffff80
	s_nop 0
	global_load_lds_dwordx4 v2, s[54:55] offset:128
	s_add_i32 m0, s64, 0xffffff80
	s_nop 0
	global_load_lds_dwordx4 v168, s[54:55] offset:128
	s_waitcnt vmcnt(8)
	s_waitcnt lgkmcnt(0)
	s_barrier
	v_mfma_f32_16x16x32_bf16 v[58:61], v[134:137], v[184:187], v[58:61]
	v_mfma_f32_16x16x32_bf16 v[58:61], v[138:141], v[190:193], v[58:61]
	v_mfma_f32_16x16x32_bf16 v[54:57], v[142:145], v[184:187], v[54:57]
	v_mfma_f32_16x16x32_bf16 v[54:57], v[146:149], v[190:193], v[54:57]
	v_mfma_f32_16x16x32_bf16 v[66:69], v[150:153], v[184:187], v[66:69]
	v_mfma_f32_16x16x32_bf16 v[66:69], v[154:157], v[190:193], v[66:69]
	v_mfma_f32_16x16x32_bf16 v[62:65], v[176:179], v[184:187], v[62:65]
	v_mfma_f32_16x16x32_bf16 v[62:65], v[180:183], v[190:193], v[62:65]
	v_mfma_f32_16x16x32_bf16 v[38:41], v[176:179], v[212:215], v[38:41]
	v_mfma_f32_16x16x32_bf16 v[38:41], v[180:183], v[216:219], v[38:41]
	v_mfma_f32_16x16x32_bf16 v[42:45], v[150:153], v[212:215], v[42:45]
	v_mfma_f32_16x16x32_bf16 v[42:45], v[154:157], v[216:219], v[42:45]
	v_mfma_f32_16x16x32_bf16 v[46:49], v[142:145], v[212:215], v[46:49]
	v_mfma_f32_16x16x32_bf16 v[46:49], v[146:149], v[216:219], v[46:49]
	v_mfma_f32_16x16x32_bf16 v[50:53], v[134:137], v[212:215], v[50:53]
	v_mfma_f32_16x16x32_bf16 v[50:53], v[138:141], v[216:219], v[50:53]
	v_mfma_f32_16x16x32_bf16 v[34:37], v[134:137], v[220:223], v[34:37]
	v_mfma_f32_16x16x32_bf16 v[34:37], v[138:141], v[224:227], v[34:37]
	v_mfma_f32_16x16x32_bf16 v[30:33], v[142:145], v[220:223], v[30:33]
	v_mfma_f32_16x16x32_bf16 v[30:33], v[146:149], v[224:227], v[30:33]
	v_mfma_f32_16x16x32_bf16 v[26:29], v[150:153], v[220:223], v[26:29]
	v_mfma_f32_16x16x32_bf16 v[26:29], v[154:157], v[224:227], v[26:29]
	v_mfma_f32_16x16x32_bf16 v[22:25], v[176:179], v[220:223], v[22:25]
	v_mfma_f32_16x16x32_bf16 v[22:25], v[180:183], v[224:227], v[22:25]
	v_mfma_f32_16x16x32_bf16 v[6:9], v[176:179], v[228:231], v[6:9]
	v_mfma_f32_16x16x32_bf16 v[6:9], v[180:183], v[232:235], v[6:9]
	v_mfma_f32_16x16x32_bf16 v[10:13], v[150:153], v[228:231], v[10:13]
	v_mfma_f32_16x16x32_bf16 v[10:13], v[154:157], v[232:235], v[10:13]
	v_mfma_f32_16x16x32_bf16 v[14:17], v[142:145], v[228:231], v[14:17]
	v_mfma_f32_16x16x32_bf16 v[14:17], v[146:149], v[232:235], v[14:17]
	v_mfma_f32_16x16x32_bf16 v[18:21], v[134:137], v[228:231], v[18:21]
	v_mfma_f32_16x16x32_bf16 v[18:21], v[138:141], v[232:235], v[18:21]
	s_barrier
	s_add_i32 s20, s20, 2
	s_add_u32 s33, s33, 0x100
	s_addc_u32 s69, s69, 0
	s_cmpk_gt_u32 s20, 0x55
	s_mov_b64 s[22:23], s[50:51]
	s_cbranch_scc0 .LBB0_299
	s_and_b64 vcc, exec, s[46:47]
	s_cbranch_vccz .LBB0_302
	s_barrier

; #define PG8_STAGE(bufoff, gbase, voff) do { _Pragma("unroll") for (int _i = 0; _i < 2; ++_i) \
;         __builtin_amdgcn_global_load_lds((const unsigned*)((const char*)(gbase) + (voff)[_i]), (PG8_LAS unsigned*)(lds + (bufoff) + ldsw + _i * 8192), 16, 0, 0); } while (0)
; #define PG8_LDA(dst, b, h) do { _Pragma("unroll") for (int m = 0; m < 4; ++m) _Pragma("unroll") for (int k = 0; k < 2; ++k) dst[m][k] = *(const PG8_LAS bf16x8*)(lds + PG8_SA(b, h) + aoff + m * 2048 + k * 1024); } while (0)
; #define PG8_LDB(dst, b, h) do { _Pragma("unroll") for (int n = 0; n < 2; ++n) _Pragma("unroll") for (int k = 0; k < 2; ++k) dst[n][k] = *(const PG8_LAS bf16x8*)(lds + PG8_SB(b, h) + boff + n * 2048 + k * 1024); } while (0)
; #define PG8_MMA(ai, bj, At, Bt) do { __builtin_amdgcn_s_setprio(1); _Pragma("unroll") for (int m = 0; m < 4; ++m) _Pragma("unroll") for (int n = 0; n < 2; ++n) _Pragma("unroll") for (int k = 0; k < 2; ++k) \
;         acc[ai][bj][m][n] = __builtin_amdgcn_mfma_f32_16x16x32_bf16(Bt[n][k], At[m][k], acc[ai][bj][m][n], 0, 0, 0); __builtin_amdgcn_s_setprio(0); } while (0)
; #define PG8_WAIT_V(n) asm volatile("s_waitcnt vmcnt(" #n ")" ::: "memory")
; #define PG8_WAIT_L(n) asm volatile("s_waitcnt lgkmcnt(" #n ")" ::: "memory")
; template <class Epi, class Sched, bool ALIGN_EPI = false, bool SP2 = false>
; __device__ __forceinline__ void gemm_phase(PG8_LAS unsigned char* lds, const Gemm g, const Sched& S, const Epi& E) {
;     ...
;             const bool last = (t == nt - 2);
;             const char* a1 = cA + (size_t)(t + 1) * kstep;
;             const char* a2 = last ? nA : cA + (size_t)(t + 2) * kstep; const char* b2 = last ? nB : cB + (size_t)(t + 2) * kstep;
;             const char* a3 = a2 + kstep; const char* b3 = b2 + kstep;
;             if (last && has_next) S.a_ready(nxt);
;             if constexpr (SP2) {
;             PG8_LDB(B0, 0, 0); PG8_LDB(B1, 0, 1); PG8_SCHED; PG8_LDA(At, 0, 0); PG8_STAGE(PG8_SA(1, 1), a1 + hstep, voffA);
;             PG8_WAIT_V(8); PG8_WAIT_L(0); PG8_BAR; PG8_MMA(0, 0, At, B0); PG8_MMA(0, 1, At, B1); PG8_BAR; PG8_SCHED;
;             PG8_LDA(At, 0, 1); PG8_STAGE(PG8_SB(0, 0), b2, voffB); PG8_STAGE(PG8_SB(0, 1), b2 + hstep, voffB); PG8_STAGE(PG8_SA(0, 0), a2, voffA);
;             PG8_WAIT_V(8); PG8_WAIT_L(0); PG8_BAR; PG8_MMA(1, 0, At, B0); PG8_MMA(1, 1, At, B1); PG8_BAR; PG8_SCHED;
.LBB0_387:
	ds_read_b128 v[144:147], v156
	ds_read_b128 v[148:151], v156 offset:1024
	ds_read_b128 v[168:171], v156 offset:2048
	ds_read_b128 v[172:175], v156 offset:3072
	ds_read_b128 v[176:179], v157
	ds_read_b128 v[180:183], v157 offset:1024
	ds_read_b128 v[184:187], v157 offset:2048
	ds_read_b128 v[188:191], v157 offset:3072
	ds_read_b128 v[212:215], v155
	ds_read_b128 v[216:219], v155 offset:1024
	ds_read_b128 v[220:223], v155 offset:2048
	ds_read_b128 v[224:227], v155 offset:3072
	ds_read_b128 v[228:231], v155 offset:4096
	ds_read_b128 v[232:235], v155 offset:5120
	ds_read_b128 v[236:239], v155 offset:6144
	ds_read_b128 v[240:243], v155 offset:7168
	s_add_i32 m0, s60, 0xc000
	s_add_u32 s4, s56, 0xfff80080
	s_addc_u32 s5, s57, -1
	global_load_lds_dwordx4 v140, s[56:57]
	s_add_i32 m0, s60, 0xe000
	s_add_i32 s6, 0, 0x10000
	global_load_lds_dwordx4 v142, s[56:57]
	s_cmp_eq_u32 s20, 28
	s_cselect_b32 s59, s47, s5
	s_cselect_b32 s58, s75, s4
	s_cselect_b32 s55, s49, s77
	s_cselect_b32 s54, vcc_lo, s71
	s_waitcnt vmcnt(8)
	s_waitcnt lgkmcnt(0)
	s_barrier
	v_mfma_f32_16x16x32_bf16 v[122:125], v[144:147], v[212:215], v[122:125]
	v_mfma_f32_16x16x32_bf16 v[122:125], v[148:151], v[216:219], v[122:125]
	v_mfma_f32_16x16x32_bf16 v[118:121], v[168:171], v[212:215], v[118:121]
	v_mfma_f32_16x16x32_bf16 v[118:121], v[172:175], v[216:219], v[118:121]
	v_mfma_f32_16x16x32_bf16 v[130:133], v[176:179], v[212:215], v[130:133]
	v_mfma_f32_16x16x32_bf16 v[130:133], v[180:183], v[216:219], v[130:133]
	v_mfma_f32_16x16x32_bf16 v[126:129], v[184:187], v[212:215], v[126:129]
	v_mfma_f32_16x16x32_bf16 v[126:129], v[188:191], v[216:219], v[126:129]
	v_mfma_f32_16x16x32_bf16 v[110:113], v[184:187], v[220:223], v[110:113]
	v_mfma_f32_16x16x32_bf16 v[110:113], v[188:191], v[224:227], v[110:113]
	v_mfma_f32_16x16x32_bf16 v[114:117], v[176:179], v[220:223], v[114:117]
	v_mfma_f32_16x16x32_bf16 v[114:117], v[180:183], v[224:227], v[114:117]
	v_mfma_f32_16x16x32_bf16 v[102:105], v[168:171], v[220:223], v[102:105]
	v_mfma_f32_16x16x32_bf16 v[102:105], v[172:175], v[224:227], v[102:105]
	v_mfma_f32_16x16x32_bf16 v[106:109], v[144:147], v[220:223], v[106:109]
	v_mfma_f32_16x16x32_bf16 v[106:109], v[148:151], v[224:227], v[106:109]
	v_mfma_f32_16x16x32_bf16 v[90:93], v[144:147], v[228:231], v[90:93]
	v_mfma_f32_16x16x32_bf16 v[90:93], v[148:151], v[232:235], v[90:93]
	v_mfma_f32_16x16x32_bf16 v[86:89], v[168:171], v[228:231], v[86:89]
	v_mfma_f32_16x16x32_bf16 v[86:89], v[172:175], v[232:235], v[86:89]
	v_mfma_f32_16x16x32_bf16 v[98:101], v[176:179], v[228:231], v[98:101]
	v_mfma_f32_16x16x32_bf16 v[98:101], v[180:183], v[232:235], v[98:101]
	v_mfma_f32_16x16x32_bf16 v[94:97], v[184:187], v[228:231], v[94:97]
	v_mfma_f32_16x16x32_bf16 v[94:97], v[188:191], v[232:235], v[94:97]
	v_mfma_f32_16x16x32_bf16 v[78:81], v[184:187], v[236:239], v[78:81]
	v_mfma_f32_16x16x32_bf16 v[78:81], v[188:191], v[240:243], v[78:81]
	v_mfma_f32_16x16x32_bf16 v[82:85], v[176:179], v[236:239], v[82:85]
	v_mfma_f32_16x16x32_bf16 v[82:85], v[180:183], v[240:243], v[82:85]
	v_mfma_f32_16x16x32_bf16 v[70:73], v[168:171], v[236:239], v[70:73]
	v_mfma_f32_16x16x32_bf16 v[70:73], v[172:175], v[240:243], v[70:73]
	v_mfma_f32_16x16x32_bf16 v[74:77], v[144:147], v[236:239], v[74:77]
	v_mfma_f32_16x16x32_bf16 v[74:77], v[148:151], v[240:243], v[74:77]
	s_barrier
	ds_read_b128 v[212:215], v155 offset:16384
	ds_read_b128 v[216:219], v155 offset:17408
	ds_read_b128 v[220:223], v155 offset:18432
	ds_read_b128 v[224:227], v155 offset:19456
	ds_read_b128 v[228:231], v155 offset:20480
	ds_read_b128 v[232:235], v155 offset:21504
	ds_read_b128 v[236:239], v155 offset:22528
	ds_read_b128 v[240:243], v155 offset:23552
	s_add_i32 s5, s6, s24
	s_mov_b32 m0, s5
	s_add_u32 s34, s54, 0x80000
	s_addc_u32 s35, s55, 0
	global_load_lds_dwordx4 v4, s[54:55]
	s_add_i32 m0, s5, 0x2000
	s_add_i32 s4, s24, 0x14000
	global_load_lds_dwordx4 v2, s[54:55]
	s_mov_b32 m0, s4
	s_nop 0
	global_load_lds_dwordx4 v4, s[34:35]
	s_add_i32 m0, s4, 0x2000
	s_nop 0
	global_load_lds_dwordx4 v2, s[34:35]
	s_mov_b32 m0, s60
	s_nop 0
	global_load_lds_dwordx4 v136, s[58:59]
	s_mov_b32 m0, s61
	s_nop 0
	global_load_lds_dwordx4 v134, s[58:59]
	s_waitcnt vmcnt(8)
	s_waitcnt lgkmcnt(0)
	s_barrier
	v_mfma_f32_16x16x32_bf16 v[58:61], v[144:147], v[212:215], v[58:61]
	v_mfma_f32_16x16x32_bf16 v[58:61], v[148:151], v[216:219], v[58:61]
	v_mfma_f32_16x16x32_bf16 v[54:57], v[168:171], v[212:215], v[54:57]
	v_mfma_f32_16x16x32_bf16 v[54:57], v[172:175], v[216:219], v[54:57]
	v_mfma_f32_16x16x32_bf16 v[66:69], v[176:179], v[212:215], v[66:69]
	v_mfma_f32_16x16x32_bf16 v[66:69], v[180:183], v[216:219], v[66:69]
	v_mfma_f32_16x16x32_bf16 v[62:65], v[184:187], v[212:215], v[62:65]
	v_mfma_f32_16x16x32_bf16 v[62:65], v[188:191], v[216:219], v[62:65]
	v_mfma_f32_16x16x32_bf16 v[46:49], v[184:187], v[220:223], v[46:49]
	v_mfma_f32_16x16x32_bf16 v[46:49], v[188:191], v[224:227], v[46:49]
	v_mfma_f32_16x16x32_bf16 v[50:53], v[176:179], v[220:223], v[50:53]
	v_mfma_f32_16x16x32_bf16 v[50:53], v[180:183], v[224:227], v[50:53]
	v_mfma_f32_16x16x32_bf16 v[38:41], v[168:171], v[220:223], v[38:41]
	v_mfma_f32_16x16x32_bf16 v[38:41], v[172:175], v[224:227], v[38:41]
	v_mfma_f32_16x16x32_bf16 v[42:45], v[144:147], v[220:223], v[42:45]
	v_mfma_f32_16x16x32_bf16 v[42:45], v[148:151], v[224:227], v[42:45]
	v_mfma_f32_16x16x32_bf16 v[26:29], v[144:147], v[228:231], v[26:29]
	v_mfma_f32_16x16x32_bf16 v[26:29], v[148:151], v[232:235], v[26:29]
	v_mfma_f32_16x16x32_bf16 v[22:25], v[168:171], v[228:231], v[22:25]
	v_mfma_f32_16x16x32_bf16 v[22:25], v[172:175], v[232:235], v[22:25]
	v_mfma_f32_16x16x32_bf16 v[34:37], v[176:179], v[228:231], v[34:37]
	v_mfma_f32_16x16x32_bf16 v[34:37], v[180:183], v[232:235], v[34:37]
	v_mfma_f32_16x16x32_bf16 v[30:33], v[184:187], v[228:231], v[30:33]
	v_mfma_f32_16x16x32_bf16 v[30:33], v[188:191], v[232:235], v[30:33]
	v_mfma_f32_16x16x32_bf16 v[18:21], v[184:187], v[236:239], v[18:21]
	v_mfma_f32_16x16x32_bf16 v[18:21], v[188:191], v[240:243], v[18:21]
	v_mfma_f32_16x16x32_bf16 v[14:17], v[176:179], v[236:239], v[14:17]
	v_mfma_f32_16x16x32_bf16 v[14:17], v[180:183], v[240:243], v[14:17]
	v_mfma_f32_16x16x32_bf16 v[6:9], v[168:171], v[236:239], v[6:9]
	v_mfma_f32_16x16x32_bf16 v[6:9], v[172:175], v[240:243], v[6:9]
	v_mfma_f32_16x16x32_bf16 v[10:13], v[144:147], v[236:239], v[10:13]
	v_mfma_f32_16x16x32_bf16 v[10:13], v[148:151], v[240:243], v[10:13]
	s_barrier
; #define PG8_STAGE(bufoff, gbase, voff) do { _Pragma("unroll") for (int _i = 0; _i < 2; ++_i) \
;         __builtin_amdgcn_global_load_lds((const unsigned*)((const char*)(gbase) + (voff)[_i]), (PG8_LAS unsigned*)(lds + (bufoff) + ldsw + _i * 8192), 16, 0, 0); } while (0)
; #define PG8_LDA(dst, b, h) do { _Pragma("unroll") for (int m = 0; m < 4; ++m) _Pragma("unroll") for (int k = 0; k < 2; ++k) dst[m][k] = *(const PG8_LAS bf16x8*)(lds + PG8_SA(b, h) + aoff + m * 2048 + k * 1024); } while (0)
; #define PG8_LDB(dst, b, h) do { _Pragma("unroll") for (int n = 0; n < 2; ++n) _Pragma("unroll") for (int k = 0; k < 2; ++k) dst[n][k] = *(const PG8_LAS bf16x8*)(lds + PG8_SB(b, h) + boff + n * 2048 + k * 1024); } while (0)
; #define PG8_MMA(ai, bj, At, Bt) do { __builtin_amdgcn_s_setprio(1); _Pragma("unroll") for (int m = 0; m < 4; ++m) _Pragma("unroll") for (int n = 0; n < 2; ++n) _Pragma("unroll") for (int k = 0; k < 2; ++k) \
;         acc[ai][bj][m][n] = __builtin_amdgcn_mfma_f32_16x16x32_bf16(Bt[n][k], At[m][k], acc[ai][bj][m][n], 0, 0, 0); __builtin_amdgcn_s_setprio(0); } while (0)
; #define PG8_WAIT_V(n) asm volatile("s_waitcnt vmcnt(" #n ")" ::: "memory")
; #define PG8_WAIT_L(n) asm volatile("s_waitcnt lgkmcnt(" #n ")" ::: "memory")
; #define PG8_BAR __builtin_amdgcn_s_barrier()
; #define PG8_SCHED __builtin_amdgcn_sched_barrier(0)
; template <class Epi, class Sched, bool ALIGN_EPI = false, bool SP2 = false>
; __device__ __forceinline__ void gemm_phase(PG8_LAS unsigned char* lds, const Gemm g, const Sched& S, const Epi& E) {
;     ...
;         for (int t = 0; t < nt; t += 2) {
;             const bool last = (t == nt - 2);
;             const char* a1 = cA + (size_t)(t + 1) * kstep;
;             const char* a2 = last ? nA : cA + (size_t)(t + 2) * kstep; const char* b2 = last ? nB : cB + (size_t)(t + 2) * kstep;
;     ...
;             PG8_LDB(B0, 1, 0); PG8_LDB(B1, 1, 1); PG8_SCHED; PG8_LDA(At, 1, 0); PG8_STAGE(PG8_SA(0, 1), a2 + hstep, voffA);
;             PG8_WAIT_V(8); PG8_WAIT_L(0); PG8_BAR; PG8_MMA(0, 0, At, B0); PG8_MMA(0, 1, At, B1); PG8_BAR; PG8_SCHED;
;             PG8_LDA(At, 1, 1); PG8_STAGE(PG8_SB(1, 0), b3, voffB); PG8_STAGE(PG8_SB(1, 1), b3 + hstep, voffB); PG8_STAGE(PG8_SA(1, 0), a3, voffA);
;             PG8_WAIT_V(8); PG8_WAIT_L(0); PG8_BAR; PG8_MMA(1, 0, At, B0); PG8_MMA(1, 1, At, B1); PG8_BAR; PG8_SCHED;
	ds_read_b128 v[144:147], v192
	ds_read_b128 v[148:151], v192 offset:1024
	ds_read_b128 v[168:171], v192 offset:2048
	ds_read_b128 v[172:175], v192 offset:3072
	ds_read_b128 v[176:179], v193
	ds_read_b128 v[180:183], v193 offset:1024
	ds_read_b128 v[184:187], v193 offset:2048
	ds_read_b128 v[188:191], v193 offset:3072
	ds_read_b128 v[212:215], v155 offset:32768
	ds_read_b128 v[216:219], v155 offset:33792
	ds_read_b128 v[220:223], v155 offset:34816
	ds_read_b128 v[224:227], v155 offset:35840
	ds_read_b128 v[228:231], v155 offset:36864
	ds_read_b128 v[232:235], v155 offset:37888
	ds_read_b128 v[236:239], v155 offset:38912
	ds_read_b128 v[240:243], v155 offset:39936
	s_add_u32 s34, s58, 0x80000
	s_addc_u32 s35, s59, 0
	s_mov_b32 m0, s64
	global_load_lds_dwordx4 v136, s[34:35]
	s_mov_b32 m0, s65
	s_add_i32 s5, 0, 0x1c000
	global_load_lds_dwordx4 v134, s[34:35]
	s_waitcnt vmcnt(8)
	s_waitcnt lgkmcnt(0)
	s_barrier
	v_mfma_f32_16x16x32_bf16 v[122:125], v[144:147], v[212:215], v[122:125]
	v_mfma_f32_16x16x32_bf16 v[122:125], v[148:151], v[216:219], v[122:125]
	v_mfma_f32_16x16x32_bf16 v[118:121], v[168:171], v[212:215], v[118:121]
	v_mfma_f32_16x16x32_bf16 v[118:121], v[172:175], v[216:219], v[118:121]
	v_mfma_f32_16x16x32_bf16 v[130:133], v[176:179], v[212:215], v[130:133]
	v_mfma_f32_16x16x32_bf16 v[130:133], v[180:183], v[216:219], v[130:133]
	v_mfma_f32_16x16x32_bf16 v[126:129], v[184:187], v[212:215], v[126:129]
	v_mfma_f32_16x16x32_bf16 v[126:129], v[188:191], v[216:219], v[126:129]
	v_mfma_f32_16x16x32_bf16 v[110:113], v[184:187], v[220:223], v[110:113]
	v_mfma_f32_16x16x32_bf16 v[110:113], v[188:191], v[224:227], v[110:113]
	v_mfma_f32_16x16x32_bf16 v[114:117], v[176:179], v[220:223], v[114:117]
	v_mfma_f32_16x16x32_bf16 v[114:117], v[180:183], v[224:227], v[114:117]
	v_mfma_f32_16x16x32_bf16 v[102:105], v[168:171], v[220:223], v[102:105]
	v_mfma_f32_16x16x32_bf16 v[102:105], v[172:175], v[224:227], v[102:105]
	v_mfma_f32_16x16x32_bf16 v[106:109], v[144:147], v[220:223], v[106:109]
	v_mfma_f32_16x16x32_bf16 v[106:109], v[148:151], v[224:227], v[106:109]
	v_mfma_f32_16x16x32_bf16 v[90:93], v[144:147], v[228:231], v[90:93]
	v_mfma_f32_16x16x32_bf16 v[90:93], v[148:151], v[232:235], v[90:93]
	v_mfma_f32_16x16x32_bf16 v[86:89], v[168:171], v[228:231], v[86:89]
	v_mfma_f32_16x16x32_bf16 v[86:89], v[172:175], v[232:235], v[86:89]
	v_mfma_f32_16x16x32_bf16 v[98:101], v[176:179], v[228:231], v[98:101]
	v_mfma_f32_16x16x32_bf16 v[98:101], v[180:183], v[232:235], v[98:101]
	v_mfma_f32_16x16x32_bf16 v[94:97], v[184:187], v[228:231], v[94:97]
	v_mfma_f32_16x16x32_bf16 v[94:97], v[188:191], v[232:235], v[94:97]
	v_mfma_f32_16x16x32_bf16 v[78:81], v[184:187], v[236:239], v[78:81]
	v_mfma_f32_16x16x32_bf16 v[78:81], v[188:191], v[240:243], v[78:81]
	v_mfma_f32_16x16x32_bf16 v[82:85], v[176:179], v[236:239], v[82:85]
	v_mfma_f32_16x16x32_bf16 v[82:85], v[180:183], v[240:243], v[82:85]
	v_mfma_f32_16x16x32_bf16 v[70:73], v[168:171], v[236:239], v[70:73]
	v_mfma_f32_16x16x32_bf16 v[70:73], v[172:175], v[240:243], v[70:73]
	v_mfma_f32_16x16x32_bf16 v[74:77], v[144:147], v[236:239], v[74:77]
	v_mfma_f32_16x16x32_bf16 v[74:77], v[148:151], v[240:243], v[74:77]
	s_barrier
	ds_read_b128 v[212:215], v155 offset:49152
	ds_read_b128 v[216:219], v155 offset:50176
	ds_read_b128 v[220:223], v155 offset:51200
	ds_read_b128 v[224:227], v155 offset:52224
	ds_read_b128 v[228:231], v155 offset:53248
	ds_read_b128 v[232:235], v155 offset:54272
	ds_read_b128 v[236:239], v155 offset:55296
	ds_read_b128 v[240:243], v155 offset:56320
	s_add_i32 s4, s24, 0x18000
	s_add_i32 m0, s4, 0xffffff80
	s_nop 0
	global_load_lds_dwordx4 v4, s[54:55] offset:128
	s_add_i32 m0, s4, 0x1f80
	s_add_i32 s4, s5, s24
	global_load_lds_dwordx4 v2, s[54:55] offset:128
	s_add_u32 s34, s54, 0x80080
	s_addc_u32 s35, s55, 0
	s_mov_b32 m0, s4
	s_nop 0
	global_load_lds_dwordx4 v4, s[34:35]
	s_add_i32 m0, s4, 0x2000
	s_nop 0
	global_load_lds_dwordx4 v2, s[34:35]
	s_add_i32 m0, s67, 0xffffff80
	s_nop 0
	global_load_lds_dwordx4 v136, s[58:59] offset:128
	s_add_i32 m0, s72, 0xffffff80
	s_nop 0
	global_load_lds_dwordx4 v134, s[58:59] offset:128
	s_waitcnt vmcnt(8)
	s_waitcnt lgkmcnt(0)
	s_barrier
	v_mfma_f32_16x16x32_bf16 v[58:61], v[144:147], v[212:215], v[58:61]
	v_mfma_f32_16x16x32_bf16 v[58:61], v[148:151], v[216:219], v[58:61]
	v_mfma_f32_16x16x32_bf16 v[54:57], v[168:171], v[212:215], v[54:57]
	v_mfma_f32_16x16x32_bf16 v[54:57], v[172:175], v[216:219], v[54:57]
	v_mfma_f32_16x16x32_bf16 v[66:69], v[176:179], v[212:215], v[66:69]
	v_mfma_f32_16x16x32_bf16 v[66:69], v[180:183], v[216:219], v[66:69]
	v_mfma_f32_16x16x32_bf16 v[62:65], v[184:187], v[212:215], v[62:65]
	v_mfma_f32_16x16x32_bf16 v[62:65], v[188:191], v[216:219], v[62:65]
	v_mfma_f32_16x16x32_bf16 v[46:49], v[184:187], v[220:223], v[46:49]
	v_mfma_f32_16x16x32_bf16 v[46:49], v[188:191], v[224:227], v[46:49]
	v_mfma_f32_16x16x32_bf16 v[50:53], v[176:179], v[220:223], v[50:53]
	v_mfma_f32_16x16x32_bf16 v[50:53], v[180:183], v[224:227], v[50:53]
	v_mfma_f32_16x16x32_bf16 v[38:41], v[168:171], v[220:223], v[38:41]
	v_mfma_f32_16x16x32_bf16 v[38:41], v[172:175], v[224:227], v[38:41]
	v_mfma_f32_16x16x32_bf16 v[42:45], v[144:147], v[220:223], v[42:45]
	v_mfma_f32_16x16x32_bf16 v[42:45], v[148:151], v[224:227], v[42:45]
	v_mfma_f32_16x16x32_bf16 v[26:29], v[144:147], v[228:231], v[26:29]
	v_mfma_f32_16x16x32_bf16 v[26:29], v[148:151], v[232:235], v[26:29]
	v_mfma_f32_16x16x32_bf16 v[22:25], v[168:171], v[228:231], v[22:25]
	v_mfma_f32_16x16x32_bf16 v[22:25], v[172:175], v[232:235], v[22:25]
	v_mfma_f32_16x16x32_bf16 v[34:37], v[176:179], v[228:231], v[34:37]
	v_mfma_f32_16x16x32_bf16 v[34:37], v[180:183], v[232:235], v[34:37]
	v_mfma_f32_16x16x32_bf16 v[30:33], v[184:187], v[228:231], v[30:33]
	v_mfma_f32_16x16x32_bf16 v[30:33], v[188:191], v[232:235], v[30:33]
	v_mfma_f32_16x16x32_bf16 v[18:21], v[184:187], v[236:239], v[18:21]
	v_mfma_f32_16x16x32_bf16 v[18:21], v[188:191], v[240:243], v[18:21]
	v_mfma_f32_16x16x32_bf16 v[14:17], v[176:179], v[236:239], v[14:17]
	v_mfma_f32_16x16x32_bf16 v[14:17], v[180:183], v[240:243], v[14:17]
	v_mfma_f32_16x16x32_bf16 v[6:9], v[168:171], v[236:239], v[6:9]
	v_mfma_f32_16x16x32_bf16 v[6:9], v[172:175], v[240:243], v[6:9]
	v_mfma_f32_16x16x32_bf16 v[10:13], v[144:147], v[236:239], v[10:13]
	v_mfma_f32_16x16x32_bf16 v[10:13], v[148:151], v[240:243], v[10:13]
	s_barrier
	s_add_i32 s20, s20, 2
	s_add_u32 s56, s56, 0x100
	s_addc_u32 s57, s57, 0
	s_add_u32 s71, s71, 0x100
	s_addc_u32 s77, s77, 0
	s_cmp_gt_u32 s20, 29
	s_cbranch_scc0 .LBB0_387
	s_and_b64 vcc, exec, s[44:45]
	s_movk_i32 s75, 0x800
	s_movk_i32 s77, 0x6000
	s_mov_b32 s71, 0x44800000
	s_cbranch_vccz .LBB0_390
	s_barrier

; #define PG8_STAGE(bufoff, gbase, voff) do { _Pragma("unroll") for (int _i = 0; _i < 2; ++_i) \
;         __builtin_amdgcn_global_load_lds((const unsigned*)((const char*)(gbase) + (voff)[_i]), (PG8_LAS unsigned*)(lds + (bufoff) + ldsw + _i * 8192), 16, 0, 0); } while (0)
; #define PG8_LDA(dst, b, h) do { _Pragma("unroll") for (int m = 0; m < 4; ++m) _Pragma("unroll") for (int k = 0; k < 2; ++k) dst[m][k] = *(const PG8_LAS bf16x8*)(lds + PG8_SA(b, h) + aoff + m * 2048 + k * 1024); } while (0)
; #define PG8_LDB(dst, b, h) do { _Pragma("unroll") for (int n = 0; n < 2; ++n) _Pragma("unroll") for (int k = 0; k < 2; ++k) dst[n][k] = *(const PG8_LAS bf16x8*)(lds + PG8_SB(b, h) + boff + n * 2048 + k * 1024); } while (0)
; #define PG8_MMA(ai, bj, At, Bt) do { __builtin_amdgcn_s_setprio(1); _Pragma("unroll") for (int m = 0; m < 4; ++m) _Pragma("unroll") for (int n = 0; n < 2; ++n) _Pragma("unroll") for (int k = 0; k < 2; ++k) \
;         acc[ai][bj][m][n] = __builtin_amdgcn_mfma_f32_16x16x32_bf16(Bt[n][k], At[m][k], acc[ai][bj][m][n], 0, 0, 0); __builtin_amdgcn_s_setprio(0); } while (0)
; #define PG8_WAIT_V(n) asm volatile("s_waitcnt vmcnt(" #n ")" ::: "memory")
; #define PG8_WAIT_L(n) asm volatile("s_waitcnt lgkmcnt(" #n ")" ::: "memory")
; template <class Epi, class Sched, bool ALIGN_EPI = false, bool SP2 = false>
; __device__ __forceinline__ void gemm_phase(PG8_LAS unsigned char* lds, const Gemm g, const Sched& S, const Epi& E) {
;     ...
;             const bool last = (t == nt - 2);
;             const char* a1 = cA + (size_t)(t + 1) * kstep;
;             const char* a2 = last ? nA : cA + (size_t)(t + 2) * kstep; const char* b2 = last ? nB : cB + (size_t)(t + 2) * kstep;
;             const char* a3 = a2 + kstep; const char* b3 = b2 + kstep;
;             if (last && has_next) S.a_ready(nxt);
;             if constexpr (SP2) {
;             PG8_LDB(B0, 0, 0); PG8_LDB(B1, 0, 1); PG8_SCHED; PG8_LDA(At, 0, 0); PG8_STAGE(PG8_SA(1, 1), a1 + hstep, voffA);
;             PG8_WAIT_V(8); PG8_WAIT_L(0); PG8_BAR; PG8_MMA(0, 0, At, B0); PG8_MMA(0, 1, At, B1); PG8_BAR; PG8_SCHED;
;             PG8_LDA(At, 0, 1); PG8_STAGE(PG8_SB(0, 0), b2, voffB); PG8_STAGE(PG8_SB(0, 1), b2 + hstep, voffB); PG8_STAGE(PG8_SA(0, 0), a2, voffA);
;             PG8_WAIT_V(8); PG8_WAIT_L(0); PG8_BAR; PG8_MMA(1, 0, At, B0); PG8_MMA(1, 1, At, B1); PG8_BAR; PG8_SCHED;
.LBB0_1738:
	s_add_u32 s4, s50, 0xfff80080
	s_addc_u32 s5, s51, -1
	s_add_i32 s6, 0, 0x10000
	s_cmp_eq_u32 s20, 28
	s_cselect_b32 s53, s43, s5
	s_cselect_b32 s52, s66, s4
	s_cselect_b32 s49, s45, s71
	s_cselect_b32 s48, s67, s69
	ds_read_b128 v[134:137], v234
	ds_read_b128 v[138:141], v234 offset:1024
	ds_read_b128 v[142:145], v234 offset:2048
	ds_read_b128 v[146:149], v234 offset:3072
	ds_read_b128 v[150:153], v235
	ds_read_b128 v[154:157], v235 offset:1024
	ds_read_b128 v[176:179], v235 offset:2048
	ds_read_b128 v[180:183], v235 offset:3072
	s_add_i32 m0, s54, 0xc000
	ds_read_b128 v[184:187], v188
	ds_read_b128 v[190:193], v188 offset:1024
	ds_read_b128 v[210:213], v188 offset:2048
	ds_read_b128 v[214:217], v188 offset:3072
	ds_read_b128 v[218:221], v188 offset:4096
	ds_read_b128 v[222:225], v188 offset:5120
	ds_read_b128 v[226:229], v188 offset:6144
	ds_read_b128 v[230:233], v188 offset:7168
	global_load_lds_dwordx4 v172, s[50:51]
	s_add_i32 m0, s54, 0xe000
	s_nop 0
	global_load_lds_dwordx4 v174, s[50:51]
	s_waitcnt vmcnt(8)
	s_waitcnt lgkmcnt(0)
	s_barrier
	v_mfma_f32_16x16x32_bf16 v[122:125], v[134:137], v[184:187], v[122:125]
	v_mfma_f32_16x16x32_bf16 v[122:125], v[138:141], v[190:193], v[122:125]
	v_mfma_f32_16x16x32_bf16 v[118:121], v[142:145], v[184:187], v[118:121]
	v_mfma_f32_16x16x32_bf16 v[118:121], v[146:149], v[190:193], v[118:121]
	v_mfma_f32_16x16x32_bf16 v[130:133], v[150:153], v[184:187], v[130:133]
	v_mfma_f32_16x16x32_bf16 v[130:133], v[154:157], v[190:193], v[130:133]
	v_mfma_f32_16x16x32_bf16 v[126:129], v[176:179], v[184:187], v[126:129]
	v_mfma_f32_16x16x32_bf16 v[126:129], v[180:183], v[190:193], v[126:129]
	v_mfma_f32_16x16x32_bf16 v[102:105], v[176:179], v[210:213], v[102:105]
	v_mfma_f32_16x16x32_bf16 v[102:105], v[180:183], v[214:217], v[102:105]
	v_mfma_f32_16x16x32_bf16 v[110:113], v[150:153], v[210:213], v[110:113]
	v_mfma_f32_16x16x32_bf16 v[110:113], v[154:157], v[214:217], v[110:113]
	v_mfma_f32_16x16x32_bf16 v[106:109], v[142:145], v[210:213], v[106:109]
	v_mfma_f32_16x16x32_bf16 v[106:109], v[146:149], v[214:217], v[106:109]
	v_mfma_f32_16x16x32_bf16 v[114:117], v[134:137], v[210:213], v[114:117]
	v_mfma_f32_16x16x32_bf16 v[114:117], v[138:141], v[214:217], v[114:117]
	v_mfma_f32_16x16x32_bf16 v[98:101], v[134:137], v[218:221], v[98:101]
	v_mfma_f32_16x16x32_bf16 v[98:101], v[138:141], v[222:225], v[98:101]
	v_mfma_f32_16x16x32_bf16 v[90:93], v[142:145], v[218:221], v[90:93]
	v_mfma_f32_16x16x32_bf16 v[90:93], v[146:149], v[222:225], v[90:93]
	v_mfma_f32_16x16x32_bf16 v[94:97], v[150:153], v[218:221], v[94:97]
	v_mfma_f32_16x16x32_bf16 v[94:97], v[154:157], v[222:225], v[94:97]
	v_mfma_f32_16x16x32_bf16 v[86:89], v[176:179], v[218:221], v[86:89]
	v_mfma_f32_16x16x32_bf16 v[86:89], v[180:183], v[222:225], v[86:89]
	v_mfma_f32_16x16x32_bf16 v[70:73], v[176:179], v[226:229], v[70:73]
	v_mfma_f32_16x16x32_bf16 v[70:73], v[180:183], v[230:233], v[70:73]
	v_mfma_f32_16x16x32_bf16 v[78:81], v[150:153], v[226:229], v[78:81]
	v_mfma_f32_16x16x32_bf16 v[78:81], v[154:157], v[230:233], v[78:81]
	v_mfma_f32_16x16x32_bf16 v[74:77], v[142:145], v[226:229], v[74:77]
	v_mfma_f32_16x16x32_bf16 v[74:77], v[146:149], v[230:233], v[74:77]
	v_mfma_f32_16x16x32_bf16 v[82:85], v[134:137], v[226:229], v[82:85]
	v_mfma_f32_16x16x32_bf16 v[82:85], v[138:141], v[230:233], v[82:85]
	s_barrier
	s_add_i32 s5, s6, s24
	s_mov_b32 m0, s5
	ds_read_b128 v[184:187], v188 offset:16384
	ds_read_b128 v[190:193], v188 offset:17408
	ds_read_b128 v[210:213], v188 offset:18432
	ds_read_b128 v[214:217], v188 offset:19456
	ds_read_b128 v[218:221], v188 offset:20480
	ds_read_b128 v[222:225], v188 offset:21504
	ds_read_b128 v[226:229], v188 offset:22528
	ds_read_b128 v[230:233], v188 offset:23552
	global_load_lds_dwordx4 v4, s[48:49]
	s_add_i32 m0, s5, 0x2000
	s_add_u32 s34, s48, 0x80000
	s_addc_u32 s35, s49, 0
	s_add_i32 s4, s24, 0x14000
	global_load_lds_dwordx4 v2, s[48:49]
	s_mov_b32 m0, s4
	s_nop 0
	global_load_lds_dwordx4 v4, s[34:35]
	s_add_i32 m0, s4, 0x2000
	s_nop 0
	global_load_lds_dwordx4 v2, s[34:35]
	s_mov_b32 m0, s54
	s_nop 0
	global_load_lds_dwordx4 v170, s[52:53]
	s_mov_b32 m0, s55
	s_nop 0
	global_load_lds_dwordx4 v168, s[52:53]
	s_waitcnt vmcnt(8)
	s_waitcnt lgkmcnt(0)
	s_barrier
	v_mfma_f32_16x16x32_bf16 v[58:61], v[134:137], v[184:187], v[58:61]
	v_mfma_f32_16x16x32_bf16 v[58:61], v[138:141], v[190:193], v[58:61]
	v_mfma_f32_16x16x32_bf16 v[54:57], v[142:145], v[184:187], v[54:57]
	v_mfma_f32_16x16x32_bf16 v[54:57], v[146:149], v[190:193], v[54:57]
	v_mfma_f32_16x16x32_bf16 v[66:69], v[150:153], v[184:187], v[66:69]
	v_mfma_f32_16x16x32_bf16 v[66:69], v[154:157], v[190:193], v[66:69]
	v_mfma_f32_16x16x32_bf16 v[62:65], v[176:179], v[184:187], v[62:65]
	v_mfma_f32_16x16x32_bf16 v[62:65], v[180:183], v[190:193], v[62:65]
	v_mfma_f32_16x16x32_bf16 v[38:41], v[176:179], v[210:213], v[38:41]
	v_mfma_f32_16x16x32_bf16 v[38:41], v[180:183], v[214:217], v[38:41]
	v_mfma_f32_16x16x32_bf16 v[46:49], v[150:153], v[210:213], v[46:49]
	v_mfma_f32_16x16x32_bf16 v[46:49], v[154:157], v[214:217], v[46:49]
	v_mfma_f32_16x16x32_bf16 v[42:45], v[142:145], v[210:213], v[42:45]
	v_mfma_f32_16x16x32_bf16 v[42:45], v[146:149], v[214:217], v[42:45]
	v_mfma_f32_16x16x32_bf16 v[50:53], v[134:137], v[210:213], v[50:53]
	v_mfma_f32_16x16x32_bf16 v[50:53], v[138:141], v[214:217], v[50:53]
	v_mfma_f32_16x16x32_bf16 v[34:37], v[134:137], v[218:221], v[34:37]
	v_mfma_f32_16x16x32_bf16 v[34:37], v[138:141], v[222:225], v[34:37]
	v_mfma_f32_16x16x32_bf16 v[26:29], v[142:145], v[218:221], v[26:29]
	v_mfma_f32_16x16x32_bf16 v[26:29], v[146:149], v[222:225], v[26:29]
	v_mfma_f32_16x16x32_bf16 v[30:33], v[150:153], v[218:221], v[30:33]
	v_mfma_f32_16x16x32_bf16 v[30:33], v[154:157], v[222:225], v[30:33]
	v_mfma_f32_16x16x32_bf16 v[22:25], v[176:179], v[218:221], v[22:25]
	v_mfma_f32_16x16x32_bf16 v[22:25], v[180:183], v[222:225], v[22:25]
	v_mfma_f32_16x16x32_bf16 v[6:9], v[176:179], v[226:229], v[6:9]
	v_mfma_f32_16x16x32_bf16 v[6:9], v[180:183], v[230:233], v[6:9]
	v_mfma_f32_16x16x32_bf16 v[14:17], v[150:153], v[226:229], v[14:17]
	v_mfma_f32_16x16x32_bf16 v[14:17], v[154:157], v[230:233], v[14:17]
	v_mfma_f32_16x16x32_bf16 v[10:13], v[142:145], v[226:229], v[10:13]
	v_mfma_f32_16x16x32_bf16 v[10:13], v[146:149], v[230:233], v[10:13]
	v_mfma_f32_16x16x32_bf16 v[18:21], v[134:137], v[226:229], v[18:21]
	v_mfma_f32_16x16x32_bf16 v[18:21], v[138:141], v[230:233], v[18:21]
	s_barrier
; #define PG8_STAGE(bufoff, gbase, voff) do { _Pragma("unroll") for (int _i = 0; _i < 2; ++_i) \
;         __builtin_amdgcn_global_load_lds((const unsigned*)((const char*)(gbase) + (voff)[_i]), (PG8_LAS unsigned*)(lds + (bufoff) + ldsw + _i * 8192), 16, 0, 0); } while (0)
; #define PG8_LDA(dst, b, h) do { _Pragma("unroll") for (int m = 0; m < 4; ++m) _Pragma("unroll") for (int k = 0; k < 2; ++k) dst[m][k] = *(const PG8_LAS bf16x8*)(lds + PG8_SA(b, h) + aoff + m * 2048 + k * 1024); } while (0)
; #define PG8_LDB(dst, b, h) do { _Pragma("unroll") for (int n = 0; n < 2; ++n) _Pragma("unroll") for (int k = 0; k < 2; ++k) dst[n][k] = *(const PG8_LAS bf16x8*)(lds + PG8_SB(b, h) + boff + n * 2048 + k * 1024); } while (0)
; #define PG8_MMA(ai, bj, At, Bt) do { __builtin_amdgcn_s_setprio(1); _Pragma("unroll") for (int m = 0; m < 4; ++m) _Pragma("unroll") for (int n = 0; n < 2; ++n) _Pragma("unroll") for (int k = 0; k < 2; ++k) \
;         acc[ai][bj][m][n] = __builtin_amdgcn_mfma_f32_16x16x32_bf16(Bt[n][k], At[m][k], acc[ai][bj][m][n], 0, 0, 0); __builtin_amdgcn_s_setprio(0); } while (0)
; #define PG8_WAIT_V(n) asm volatile("s_waitcnt vmcnt(" #n ")" ::: "memory")
; #define PG8_WAIT_L(n) asm volatile("s_waitcnt lgkmcnt(" #n ")" ::: "memory")
; #define PG8_BAR __builtin_amdgcn_s_barrier()
; #define PG8_SCHED __builtin_amdgcn_sched_barrier(0)
; template <class Epi, class Sched, bool ALIGN_EPI = false, bool SP2 = false>
; __device__ __forceinline__ void gemm_phase(PG8_LAS unsigned char* lds, const Gemm g, const Sched& S, const Epi& E) {
;     ...
;         for (int t = 0; t < nt; t += 2) {
;             const bool last = (t == nt - 2);
;             const char* a1 = cA + (size_t)(t + 1) * kstep;
;             const char* a2 = last ? nA : cA + (size_t)(t + 2) * kstep; const char* b2 = last ? nB : cB + (size_t)(t + 2) * kstep;
;     ...
;             PG8_LDB(B0, 1, 0); PG8_LDB(B1, 1, 1); PG8_SCHED; PG8_LDA(At, 1, 0); PG8_STAGE(PG8_SA(0, 1), a2 + hstep, voffA);
;             PG8_WAIT_V(8); PG8_WAIT_L(0); PG8_BAR; PG8_MMA(0, 0, At, B0); PG8_MMA(0, 1, At, B1); PG8_BAR; PG8_SCHED;
;             PG8_LDA(At, 1, 1); PG8_STAGE(PG8_SB(1, 0), b3, voffB); PG8_STAGE(PG8_SB(1, 1), b3 + hstep, voffB); PG8_STAGE(PG8_SA(1, 0), a3, voffA);
;             PG8_WAIT_V(8); PG8_WAIT_L(0); PG8_BAR; PG8_MMA(1, 0, At, B0); PG8_MMA(1, 1, At, B1); PG8_BAR; PG8_SCHED;
	s_add_i32 s5, 0, 0x1c000
	ds_read_b128 v[134:137], v236
	ds_read_b128 v[138:141], v236 offset:1024
	ds_read_b128 v[142:145], v236 offset:2048
	ds_read_b128 v[146:149], v236 offset:3072
	ds_read_b128 v[150:153], v237
	ds_read_b128 v[154:157], v237 offset:1024
	ds_read_b128 v[176:179], v237 offset:2048
	ds_read_b128 v[180:183], v237 offset:3072
	s_add_u32 s34, s52, 0x80000
	s_addc_u32 s35, s53, 0
	s_mov_b32 m0, s56
	ds_read_b128 v[184:187], v188 offset:32768
	ds_read_b128 v[190:193], v188 offset:33792
	ds_read_b128 v[210:213], v188 offset:34816
	ds_read_b128 v[214:217], v188 offset:35840
	ds_read_b128 v[218:221], v188 offset:36864
	ds_read_b128 v[222:225], v188 offset:37888
	ds_read_b128 v[226:229], v188 offset:38912
	ds_read_b128 v[230:233], v188 offset:39936
	global_load_lds_dwordx4 v170, s[34:35]
	s_mov_b32 m0, s57
	s_nop 0
	global_load_lds_dwordx4 v168, s[34:35]
	s_waitcnt vmcnt(8)
	s_waitcnt lgkmcnt(0)
	s_barrier
	v_mfma_f32_16x16x32_bf16 v[122:125], v[134:137], v[184:187], v[122:125]
	v_mfma_f32_16x16x32_bf16 v[122:125], v[138:141], v[190:193], v[122:125]
	v_mfma_f32_16x16x32_bf16 v[118:121], v[142:145], v[184:187], v[118:121]
	v_mfma_f32_16x16x32_bf16 v[118:121], v[146:149], v[190:193], v[118:121]
	v_mfma_f32_16x16x32_bf16 v[130:133], v[150:153], v[184:187], v[130:133]
	v_mfma_f32_16x16x32_bf16 v[130:133], v[154:157], v[190:193], v[130:133]
	v_mfma_f32_16x16x32_bf16 v[126:129], v[176:179], v[184:187], v[126:129]
	v_mfma_f32_16x16x32_bf16 v[126:129], v[180:183], v[190:193], v[126:129]
	v_mfma_f32_16x16x32_bf16 v[102:105], v[176:179], v[210:213], v[102:105]
	v_mfma_f32_16x16x32_bf16 v[102:105], v[180:183], v[214:217], v[102:105]
	v_mfma_f32_16x16x32_bf16 v[110:113], v[150:153], v[210:213], v[110:113]
	v_mfma_f32_16x16x32_bf16 v[110:113], v[154:157], v[214:217], v[110:113]
	v_mfma_f32_16x16x32_bf16 v[106:109], v[142:145], v[210:213], v[106:109]
	v_mfma_f32_16x16x32_bf16 v[106:109], v[146:149], v[214:217], v[106:109]
	v_mfma_f32_16x16x32_bf16 v[114:117], v[134:137], v[210:213], v[114:117]
	v_mfma_f32_16x16x32_bf16 v[114:117], v[138:141], v[214:217], v[114:117]
	v_mfma_f32_16x16x32_bf16 v[98:101], v[134:137], v[218:221], v[98:101]
	v_mfma_f32_16x16x32_bf16 v[98:101], v[138:141], v[222:225], v[98:101]
	v_mfma_f32_16x16x32_bf16 v[90:93], v[142:145], v[218:221], v[90:93]
	v_mfma_f32_16x16x32_bf16 v[90:93], v[146:149], v[222:225], v[90:93]
	v_mfma_f32_16x16x32_bf16 v[94:97], v[150:153], v[218:221], v[94:97]
	v_mfma_f32_16x16x32_bf16 v[94:97], v[154:157], v[222:225], v[94:97]
	v_mfma_f32_16x16x32_bf16 v[86:89], v[176:179], v[218:221], v[86:89]
	v_mfma_f32_16x16x32_bf16 v[86:89], v[180:183], v[222:225], v[86:89]
	v_mfma_f32_16x16x32_bf16 v[70:73], v[176:179], v[226:229], v[70:73]
	v_mfma_f32_16x16x32_bf16 v[70:73], v[180:183], v[230:233], v[70:73]
	v_mfma_f32_16x16x32_bf16 v[78:81], v[150:153], v[226:229], v[78:81]
	v_mfma_f32_16x16x32_bf16 v[78:81], v[154:157], v[230:233], v[78:81]
	v_mfma_f32_16x16x32_bf16 v[74:77], v[142:145], v[226:229], v[74:77]
	v_mfma_f32_16x16x32_bf16 v[74:77], v[146:149], v[230:233], v[74:77]
	v_mfma_f32_16x16x32_bf16 v[82:85], v[134:137], v[226:229], v[82:85]
	v_mfma_f32_16x16x32_bf16 v[82:85], v[138:141], v[230:233], v[82:85]
	s_barrier
	s_add_i32 s4, s24, 0x18000
	s_add_i32 m0, s4, 0xffffff80
	ds_read_b128 v[184:187], v188 offset:49152
	ds_read_b128 v[190:193], v188 offset:50176
	ds_read_b128 v[210:213], v188 offset:51200
	ds_read_b128 v[214:217], v188 offset:52224
	ds_read_b128 v[218:221], v188 offset:53248
	ds_read_b128 v[222:225], v188 offset:54272
	ds_read_b128 v[226:229], v188 offset:55296
	ds_read_b128 v[230:233], v188 offset:56320
	global_load_lds_dwordx4 v4, s[48:49] offset:128
	s_add_i32 m0, s4, 0x1f80
	s_add_u32 s34, s48, 0x80080
	s_addc_u32 s35, s49, 0
	s_add_i32 s4, s5, s24
	global_load_lds_dwordx4 v2, s[48:49] offset:128
	s_mov_b32 m0, s4
	s_nop 0
	global_load_lds_dwordx4 v4, s[34:35]
	s_add_i32 m0, s4, 0x2000
	s_nop 0
	global_load_lds_dwordx4 v2, s[34:35]
	s_add_i32 m0, s60, 0xffffff80
	s_nop 0
	global_load_lds_dwordx4 v170, s[52:53] offset:128
	s_add_i32 m0, s61, 0xffffff80
	s_nop 0
	global_load_lds_dwordx4 v168, s[52:53] offset:128
	s_waitcnt vmcnt(8)
	s_waitcnt lgkmcnt(0)
	s_barrier
	v_mfma_f32_16x16x32_bf16 v[58:61], v[134:137], v[184:187], v[58:61]
	v_mfma_f32_16x16x32_bf16 v[58:61], v[138:141], v[190:193], v[58:61]
	v_mfma_f32_16x16x32_bf16 v[54:57], v[142:145], v[184:187], v[54:57]
	v_mfma_f32_16x16x32_bf16 v[54:57], v[146:149], v[190:193], v[54:57]
	v_mfma_f32_16x16x32_bf16 v[66:69], v[150:153], v[184:187], v[66:69]
	v_mfma_f32_16x16x32_bf16 v[66:69], v[154:157], v[190:193], v[66:69]
	v_mfma_f32_16x16x32_bf16 v[62:65], v[176:179], v[184:187], v[62:65]
	v_mfma_f32_16x16x32_bf16 v[62:65], v[180:183], v[190:193], v[62:65]
	v_mfma_f32_16x16x32_bf16 v[38:41], v[176:179], v[210:213], v[38:41]
	v_mfma_f32_16x16x32_bf16 v[38:41], v[180:183], v[214:217], v[38:41]
	v_mfma_f32_16x16x32_bf16 v[46:49], v[150:153], v[210:213], v[46:49]
	v_mfma_f32_16x16x32_bf16 v[46:49], v[154:157], v[214:217], v[46:49]
	v_mfma_f32_16x16x32_bf16 v[42:45], v[142:145], v[210:213], v[42:45]
	v_mfma_f32_16x16x32_bf16 v[42:45], v[146:149], v[214:217], v[42:45]
	v_mfma_f32_16x16x32_bf16 v[50:53], v[134:137], v[210:213], v[50:53]
	v_mfma_f32_16x16x32_bf16 v[50:53], v[138:141], v[214:217], v[50:53]
	v_mfma_f32_16x16x32_bf16 v[34:37], v[134:137], v[218:221], v[34:37]
	v_mfma_f32_16x16x32_bf16 v[34:37], v[138:141], v[222:225], v[34:37]
	v_mfma_f32_16x16x32_bf16 v[26:29], v[142:145], v[218:221], v[26:29]
	v_mfma_f32_16x16x32_bf16 v[26:29], v[146:149], v[222:225], v[26:29]
	v_mfma_f32_16x16x32_bf16 v[30:33], v[150:153], v[218:221], v[30:33]
	v_mfma_f32_16x16x32_bf16 v[30:33], v[154:157], v[222:225], v[30:33]
	v_mfma_f32_16x16x32_bf16 v[22:25], v[176:179], v[218:221], v[22:25]
	v_mfma_f32_16x16x32_bf16 v[22:25], v[180:183], v[222:225], v[22:25]
	v_mfma_f32_16x16x32_bf16 v[6:9], v[176:179], v[226:229], v[6:9]
	v_mfma_f32_16x16x32_bf16 v[6:9], v[180:183], v[230:233], v[6:9]
	v_mfma_f32_16x16x32_bf16 v[14:17], v[150:153], v[226:229], v[14:17]
	v_mfma_f32_16x16x32_bf16 v[14:17], v[154:157], v[230:233], v[14:17]
	v_mfma_f32_16x16x32_bf16 v[10:13], v[142:145], v[226:229], v[10:13]
	v_mfma_f32_16x16x32_bf16 v[10:13], v[146:149], v[230:233], v[10:13]
	v_mfma_f32_16x16x32_bf16 v[18:21], v[134:137], v[226:229], v[18:21]
	v_mfma_f32_16x16x32_bf16 v[18:21], v[138:141], v[230:233], v[18:21]
	s_barrier
	s_add_i32 s20, s20, 2
	s_add_u32 s50, s50, 0x100
	s_addc_u32 s51, s51, 0
	s_add_u32 s69, s69, 0x100
	s_addc_u32 s71, s71, 0
	s_cmp_gt_u32 s20, 29
	s_cbranch_scc0 .LBB0_1738
	s_and_b64 vcc, exec, s[40:41]
	s_cbranch_vccz .LBB0_1741
	s_barrier
